# v49 + static s_setprio 1 for waves 4-7 in the SwiGLU / residual / store GEMM main loops, per-segment flips deleted
# speedup vs baseline: 1.0214x; 1.0214x over previous
; DI const char* a_of(const Gemm& g, const Unit& u) { return (const char*)(g.A + (size_t)u.pz * g.zA + (size_t)u.pm * BM * g.lda); }
; DI const char* b_of(const Gemm& g, const Unit& u) { return (const char*)(g.Bt + (size_t)u.pz * g.zB + (size_t)u.pn * BM * g.ldb); }
; #define PG8_STAGE(bufoff, gbase, voff) do { _Pragma("unroll") for (int _i = 0; _i < 2; ++_i) \
;         __builtin_amdgcn_global_load_lds((const unsigned*)((const char*)(gbase) + (voff)[_i]), (LAS unsigned*)(lds + (bufoff) + ldsw + _i * 8192), 16, 0, 0); } while (0)
; #define PG8_LDA(dst, b, h) do { _Pragma("unroll") for (int m = 0; m < 4; ++m) _Pragma("unroll") for (int k = 0; k < 2; ++k) dst[m][k] = *(const LAS bf16x8*)(lds + PG8_SA(b, h) + aoff + m * 2048 + k * 1024); } while (0)
; #define PG8_LDB(dst, b, h) do { _Pragma("unroll") for (int n = 0; n < 2; ++n) _Pragma("unroll") for (int k = 0; k < 2; ++k) dst[n][k] = *(const LAS bf16x8*)(lds + PG8_SB(b, h) + boff + n * 2048 + k * 1024); } while (0)
; #define PG8_WAIT_V(n) asm volatile("s_waitcnt vmcnt(" #n ")" ::: "memory")
; #define PG8_WAIT_L(n) asm volatile("s_waitcnt lgkmcnt(" #n ")" ::: "memory")
; template <class Epi>
; DI void gemm_phase(LAS unsigned char* lds, int tid, const Gemm g, const Order& S, const Epi& E) {
;     ...
;         const bool has_next = S.next(ui + 1, nxt);
;         const char* nA = has_next ? a_of(g, nxt) : cA; const char* nB = has_next ? b_of(g, nxt) : cB;
; #pragma unroll 1
;         for (int t = 0; t < nt; t += 2) {
;             const bool last = (t == nt - 2);
;             const char* a1 = cA + (size_t)(t + 1) * kstep;
;             const char* a2 = last ? nA : cA + (size_t)(t + 2) * kstep; const char* b2 = last ? nB : cB + (size_t)(t + 2) * kstep;
;             const char* a3 = a2 + kstep; const char* b3 = b2 + kstep;
;             PG8_LDB(B0, 0, 0); PG8_LDB(B1, 0, 1); PG8_SCHED; PG8_LDA(At, 0, 0); PG8_STAGE(PG8_SA(1, 1), a1 + hstepA, voffA);
;             PG8_WAIT_V(8); PG8_WAIT_L(0); PG8_BAR; PG8_MMA(0, 0, At, B0); PG8_MMA(0, 1, At, B1); PG8_BAR; PG8_SCHED;
;     ...
; #pragma unroll
;         for (int a = 0; a < 2; ++a)
; #pragma unroll
;             for (int b = 0; b < 2; ++b)
; #pragma unroll
;                 for (int m = 0; m < 4; ++m)
; #pragma unroll
;                     for (int n = 0; n < 2; ++n) acc[a][b][m][n] = (f32x4){0.f, 0.f, 0.f, 0.f};
;         cur = nxt; cA = nA; cB = nB; ++ui;
.LBB0_465:
	s_add_u32 s90, s90, 0x80
	s_addc_u32 s91, s91, 0
	s_add_u32 s53, s92, 0x100
	v_mov_b32_e32 v2, 0
	s_addc_u32 vcc_lo, s93, 0
	s_mov_b32 s92, 0
	v_mov_b32_e32 v3, v2
	v_mov_b64_e32 v[4:5], v[2:3]
	v_mov_b64_e32 v[6:7], v[2:3]
	v_mov_b64_e32 v[8:9], v[2:3]
	v_mov_b64_e32 v[10:11], v[2:3]
	v_mov_b64_e32 v[12:13], v[2:3]
	v_mov_b64_e32 v[14:15], v[2:3]
	v_mov_b64_e32 v[16:17], v[2:3]
	v_mov_b64_e32 v[18:19], v[2:3]
	v_mov_b64_e32 v[20:21], v[2:3]
	v_mov_b64_e32 v[22:23], v[2:3]
	v_mov_b64_e32 v[24:25], v[2:3]
	v_mov_b64_e32 v[26:27], v[2:3]
	v_mov_b64_e32 v[28:29], v[2:3]
	v_mov_b64_e32 v[30:31], v[2:3]
	v_mov_b64_e32 v[32:33], v[2:3]
	v_mov_b64_e32 v[34:35], v[2:3]
	v_mov_b64_e32 v[36:37], v[2:3]
	v_mov_b64_e32 v[38:39], v[2:3]
	v_mov_b64_e32 v[40:41], v[2:3]
	v_mov_b64_e32 v[42:43], v[2:3]
	v_mov_b64_e32 v[44:45], v[2:3]
	v_mov_b64_e32 v[46:47], v[2:3]
	v_mov_b64_e32 v[48:49], v[2:3]
	v_mov_b64_e32 v[50:51], v[2:3]
	v_mov_b64_e32 v[52:53], v[2:3]
	v_mov_b64_e32 v[54:55], v[2:3]
	v_mov_b64_e32 v[56:57], v[2:3]
	v_mov_b64_e32 v[58:59], v[2:3]
	v_mov_b64_e32 v[60:61], v[2:3]
	v_mov_b64_e32 v[62:63], v[2:3]
	v_mov_b64_e32 v[64:65], v[2:3]
	v_mov_b64_e32 v[66:67], v[2:3]
	v_mov_b64_e32 v[68:69], v[2:3]
	v_mov_b64_e32 v[70:71], v[2:3]
	v_mov_b64_e32 v[72:73], v[2:3]
	v_mov_b64_e32 v[74:75], v[2:3]
	v_mov_b64_e32 v[76:77], v[2:3]
	v_mov_b64_e32 v[78:79], v[2:3]
	v_mov_b64_e32 v[80:81], v[2:3]
	v_mov_b64_e32 v[82:83], v[2:3]
	v_mov_b64_e32 v[84:85], v[2:3]
	v_mov_b64_e32 v[86:87], v[2:3]
	v_mov_b64_e32 v[88:89], v[2:3]
	v_mov_b64_e32 v[90:91], v[2:3]
	v_mov_b64_e32 v[92:93], v[2:3]
	v_mov_b64_e32 v[94:95], v[2:3]
	v_mov_b64_e32 v[96:97], v[2:3]
	v_mov_b64_e32 v[98:99], v[2:3]
	v_mov_b64_e32 v[100:101], v[2:3]
	v_mov_b64_e32 v[102:103], v[2:3]
	v_mov_b64_e32 v[104:105], v[2:3]
	v_mov_b64_e32 v[106:107], v[2:3]
	v_mov_b64_e32 v[108:109], v[2:3]
	v_mov_b64_e32 v[110:111], v[2:3]
	v_mov_b64_e32 v[112:113], v[2:3]
	v_mov_b64_e32 v[114:115], v[2:3]
	v_mov_b64_e32 v[116:117], v[2:3]
	v_mov_b64_e32 v[118:119], v[2:3]
	v_mov_b64_e32 v[120:121], v[2:3]
	v_mov_b64_e32 v[122:123], v[2:3]
	v_mov_b64_e32 v[124:125], v[2:3]
	v_mov_b64_e32 v[126:127], v[2:3]
	v_mov_b64_e32 v[128:129], v[2:3]
	v_readfirstlane_b32 s99, v164
	s_nop 0
	s_cmp_lt_u32 s99, 0x100
	s_cbranch_scc1 .Lprio_466
	s_setprio 1
.Lprio_466:
.LBB0_466:
	s_add_i32 vcc_hi, s92, 2
	s_add_u32 s94, s90, 0x80
	s_addc_u32 s93, s91, 0
	s_add_i32 s29, 0, 0x10000
	s_cmp_eq_u32 s45, s92
	s_cselect_b32 s93, s7, s93
	s_cselect_b32 s92, s6, s94
	v_add_u32_e32 v140, s29, v143
	s_cselect_b32 s95, s89, vcc_lo
	s_cselect_b32 s94, s88, s53
	s_add_i32 s12, 0, 0x14000
	ds_read_b128 v[146:149], v140
	ds_read_b128 v[150:153], v140 offset:1024
	ds_read_b128 v[154:157], v140 offset:2048
	ds_read_b128 v[158:161], v140 offset:3072
	v_add_u32_e32 v140, s12, v143
	ds_read_b128 v[170:173], v140
	ds_read_b128 v[174:177], v140 offset:1024
	ds_read_b128 v[196:199], v140 offset:2048
	ds_read_b128 v[200:203], v140 offset:3072
	v_lshl_add_u64 v[140:141], s[90:91], 0, v[136:137]
	s_add_i32 m0, s22, 0xc000
	ds_read_b128 v[204:207], v145
	ds_read_b128 v[208:211], v145 offset:1024
	ds_read_b128 v[212:215], v145 offset:2048
	ds_read_b128 v[216:219], v145 offset:3072
	ds_read_b128 v[220:223], v145 offset:4096
	ds_read_b128 v[224:227], v145 offset:5120
	ds_read_b128 v[228:231], v145 offset:6144
	ds_read_b128 v[232:235], v145 offset:7168
	global_load_lds_dwordx4 v[140:141], off
	v_lshl_add_u64 v[140:141], s[90:91], 0, v[138:139]
	s_add_i32 m0, s22, 0xe000
	s_nop 0
	global_load_lds_dwordx4 v[140:141], off
	s_waitcnt vmcnt(8)
	s_waitcnt lgkmcnt(0)
	s_barrier
	s_waitcnt lgkmcnt(0)
	v_mfma_f32_16x16x32_bf16 v[126:129], v[146:149], v[204:207], v[126:129]
	v_mfma_f32_16x16x32_bf16 v[122:125], v[154:157], v[204:207], v[122:125]
	v_mfma_f32_16x16x32_bf16 v[118:121], v[146:149], v[212:215], v[118:121]
	v_mfma_f32_16x16x32_bf16 v[110:113], v[154:157], v[212:215], v[110:113]
	v_mfma_f32_16x16x32_bf16 v[102:105], v[146:149], v[220:223], v[102:105]
	v_mfma_f32_16x16x32_bf16 v[94:97], v[154:157], v[220:223], v[94:97]
	v_mfma_f32_16x16x32_bf16 v[86:89], v[146:149], v[228:231], v[86:89]
	v_mfma_f32_16x16x32_bf16 v[78:81], v[154:157], v[228:231], v[78:81]
	v_mfma_f32_16x16x32_bf16 v[126:129], v[150:153], v[208:211], v[126:129]
	v_mfma_f32_16x16x32_bf16 v[122:125], v[158:161], v[208:211], v[122:125]
	v_mfma_f32_16x16x32_bf16 v[118:121], v[150:153], v[216:219], v[118:121]
	v_mfma_f32_16x16x32_bf16 v[110:113], v[158:161], v[216:219], v[110:113]
	v_mfma_f32_16x16x32_bf16 v[102:105], v[150:153], v[224:227], v[102:105]
	v_mfma_f32_16x16x32_bf16 v[94:97], v[158:161], v[224:227], v[94:97]
	v_mfma_f32_16x16x32_bf16 v[86:89], v[150:153], v[232:235], v[86:89]
	v_mfma_f32_16x16x32_bf16 v[78:81], v[158:161], v[232:235], v[78:81]
	v_mfma_f32_16x16x32_bf16 v[114:117], v[170:173], v[204:207], v[114:117]
	v_mfma_f32_16x16x32_bf16 v[106:109], v[196:199], v[204:207], v[106:109]
	v_mfma_f32_16x16x32_bf16 v[98:101], v[170:173], v[212:215], v[98:101]
	v_mfma_f32_16x16x32_bf16 v[90:93], v[196:199], v[212:215], v[90:93]
	v_mfma_f32_16x16x32_bf16 v[82:85], v[170:173], v[220:223], v[82:85]
	v_mfma_f32_16x16x32_bf16 v[74:77], v[196:199], v[220:223], v[74:77]
	v_mfma_f32_16x16x32_bf16 v[70:73], v[170:173], v[228:231], v[70:73]
	v_mfma_f32_16x16x32_bf16 v[66:69], v[196:199], v[228:231], v[66:69]
	v_mfma_f32_16x16x32_bf16 v[114:117], v[174:177], v[208:211], v[114:117]
	v_mfma_f32_16x16x32_bf16 v[106:109], v[200:203], v[208:211], v[106:109]
	v_mfma_f32_16x16x32_bf16 v[98:101], v[174:177], v[216:219], v[98:101]
	v_mfma_f32_16x16x32_bf16 v[90:93], v[200:203], v[216:219], v[90:93]
	v_mfma_f32_16x16x32_bf16 v[82:85], v[174:177], v[224:227], v[82:85]
	v_mfma_f32_16x16x32_bf16 v[74:77], v[200:203], v[224:227], v[74:77]
	v_mfma_f32_16x16x32_bf16 v[70:73], v[174:177], v[232:235], v[70:73]
	v_mfma_f32_16x16x32_bf16 v[66:69], v[200:203], v[232:235], v[66:69]
	s_barrier
; #define PG8_STAGE(bufoff, gbase, voff) do { _Pragma("unroll") for (int _i = 0; _i < 2; ++_i) \
;         __builtin_amdgcn_global_load_lds((const unsigned*)((const char*)(gbase) + (voff)[_i]), (LAS unsigned*)(lds + (bufoff) + ldsw + _i * 8192), 16, 0, 0); } while (0)
; #define PG8_LDA(dst, b, h) do { _Pragma("unroll") for (int m = 0; m < 4; ++m) _Pragma("unroll") for (int k = 0; k < 2; ++k) dst[m][k] = *(const LAS bf16x8*)(lds + PG8_SA(b, h) + aoff + m * 2048 + k * 1024); } while (0)
; #define PG8_LDB(dst, b, h) do { _Pragma("unroll") for (int n = 0; n < 2; ++n) _Pragma("unroll") for (int k = 0; k < 2; ++k) dst[n][k] = *(const LAS bf16x8*)(lds + PG8_SB(b, h) + boff + n * 2048 + k * 1024); } while (0)
; #define PG8_MMA(ai, bj, At, Bt) do { __builtin_amdgcn_s_setprio(1); _Pragma("unroll") for (int m = 0; m < 4; ++m) _Pragma("unroll") for (int n = 0; n < 2; ++n) _Pragma("unroll") for (int k = 0; k < 2; ++k) \
;         acc[ai][bj][m][n] = __builtin_amdgcn_mfma_f32_16x16x32_bf16(Bt[n][k], At[m][k], acc[ai][bj][m][n], 0, 0, 0); __builtin_amdgcn_s_setprio(0); } while (0)
; #define PG8_WAIT_V(n) asm volatile("s_waitcnt vmcnt(" #n ")" ::: "memory")
; #define PG8_WAIT_L(n) asm volatile("s_waitcnt lgkmcnt(" #n ")" ::: "memory")
; #define PG8_BAR __builtin_amdgcn_s_barrier()
; #define PG8_SCHED __builtin_amdgcn_sched_barrier(0)
; template <class Epi>
; DI void gemm_phase(LAS unsigned char* lds, int tid, const Gemm g, const Order& S, const Epi& E) {
;     ...
;             PG8_LDA(At, 0, 1); PG8_STAGE(PG8_SB(0, 0), b2, voffB); PG8_STAGE(PG8_SB(0, 1), b2 + hstepB, voffB); PG8_STAGE(PG8_SA(0, 0), a2, voffA);
;             PG8_WAIT_V(8); PG8_WAIT_L(0); PG8_BAR; PG8_MMA(1, 0, At, B0); PG8_MMA(1, 1, At, B1); PG8_BAR; PG8_SCHED;
;             PG8_LDB(B0, 1, 0); PG8_LDB(B1, 1, 1); PG8_SCHED; PG8_LDA(At, 1, 0); PG8_STAGE(PG8_SA(0, 1), a2 + hstepA, voffA);
;             PG8_WAIT_V(8); PG8_WAIT_L(0); PG8_BAR; PG8_MMA(0, 0, At, B0); PG8_MMA(0, 1, At, B1); PG8_BAR; PG8_SCHED;
	s_add_i32 s13, s29, s17
	v_lshl_add_u64 v[140:141], s[94:95], 0, v[0:1]
	s_mov_b32 m0, s13
	ds_read_b128 v[204:207], v145 offset:16384
	ds_read_b128 v[208:211], v145 offset:17408
	ds_read_b128 v[212:215], v145 offset:18432
	ds_read_b128 v[216:219], v145 offset:19456
	ds_read_b128 v[220:223], v145 offset:20480
	ds_read_b128 v[224:227], v145 offset:21504
	ds_read_b128 v[228:231], v145 offset:22528
	ds_read_b128 v[232:235], v145 offset:23552
	global_load_lds_dwordx4 v[140:141], off
	s_add_i32 m0, s13, 0x2000
	v_lshl_add_u64 v[166:167], s[94:95], 0, v[130:131]
	s_add_u32 s94, s94, s20
	s_addc_u32 s95, s95, 0
	s_add_i32 s12, s12, s17
	global_load_lds_dwordx4 v[166:167], off
	v_lshl_add_u64 v[178:179], s[94:95], 0, v[0:1]
	s_mov_b32 m0, s12
	v_lshl_add_u64 v[188:189], s[94:95], 0, v[130:131]
	global_load_lds_dwordx4 v[178:179], off
	s_add_i32 m0, s12, 0x2000
	v_lshl_add_u64 v[190:191], s[92:93], 0, v[134:135]
	global_load_lds_dwordx4 v[188:189], off
	s_mov_b32 m0, s22
	v_lshl_add_u64 v[236:237], s[92:93], 0, v[132:133]
	global_load_lds_dwordx4 v[190:191], off
	s_mov_b32 m0, s26
	s_nop 0
	global_load_lds_dwordx4 v[236:237], off
	s_waitcnt vmcnt(8)
	s_waitcnt lgkmcnt(0)
	s_barrier
	s_waitcnt lgkmcnt(0)
	v_mfma_f32_16x16x32_bf16 v[62:65], v[146:149], v[204:207], v[62:65]
	v_mfma_f32_16x16x32_bf16 v[58:61], v[154:157], v[204:207], v[58:61]
	v_mfma_f32_16x16x32_bf16 v[54:57], v[146:149], v[212:215], v[54:57]
	v_mfma_f32_16x16x32_bf16 v[46:49], v[154:157], v[212:215], v[46:49]
	v_mfma_f32_16x16x32_bf16 v[38:41], v[146:149], v[220:223], v[38:41]
	v_mfma_f32_16x16x32_bf16 v[30:33], v[154:157], v[220:223], v[30:33]
	v_mfma_f32_16x16x32_bf16 v[22:25], v[146:149], v[228:231], v[22:25]
	v_mfma_f32_16x16x32_bf16 v[14:17], v[154:157], v[228:231], v[14:17]
	v_mfma_f32_16x16x32_bf16 v[62:65], v[150:153], v[208:211], v[62:65]
	v_mfma_f32_16x16x32_bf16 v[58:61], v[158:161], v[208:211], v[58:61]
	v_mfma_f32_16x16x32_bf16 v[54:57], v[150:153], v[216:219], v[54:57]
	v_mfma_f32_16x16x32_bf16 v[46:49], v[158:161], v[216:219], v[46:49]
	v_mfma_f32_16x16x32_bf16 v[38:41], v[150:153], v[224:227], v[38:41]
	v_mfma_f32_16x16x32_bf16 v[30:33], v[158:161], v[224:227], v[30:33]
	v_mfma_f32_16x16x32_bf16 v[22:25], v[150:153], v[232:235], v[22:25]
	v_mfma_f32_16x16x32_bf16 v[14:17], v[158:161], v[232:235], v[14:17]
	v_mfma_f32_16x16x32_bf16 v[50:53], v[170:173], v[204:207], v[50:53]
	v_mfma_f32_16x16x32_bf16 v[42:45], v[196:199], v[204:207], v[42:45]
	v_mfma_f32_16x16x32_bf16 v[34:37], v[170:173], v[212:215], v[34:37]
	v_mfma_f32_16x16x32_bf16 v[26:29], v[196:199], v[212:215], v[26:29]
	v_mfma_f32_16x16x32_bf16 v[18:21], v[170:173], v[220:223], v[18:21]
	v_mfma_f32_16x16x32_bf16 v[10:13], v[196:199], v[220:223], v[10:13]
	v_mfma_f32_16x16x32_bf16 v[6:9], v[170:173], v[228:231], v[6:9]
	v_mfma_f32_16x16x32_bf16 v[2:5], v[196:199], v[228:231], v[2:5]
	v_mfma_f32_16x16x32_bf16 v[50:53], v[174:177], v[208:211], v[50:53]
	v_mfma_f32_16x16x32_bf16 v[42:45], v[200:203], v[208:211], v[42:45]
	v_mfma_f32_16x16x32_bf16 v[34:37], v[174:177], v[216:219], v[34:37]
	v_mfma_f32_16x16x32_bf16 v[26:29], v[200:203], v[216:219], v[26:29]
	v_mfma_f32_16x16x32_bf16 v[18:21], v[174:177], v[224:227], v[18:21]
	v_mfma_f32_16x16x32_bf16 v[10:13], v[200:203], v[224:227], v[10:13]
	v_mfma_f32_16x16x32_bf16 v[6:9], v[174:177], v[232:235], v[6:9]
	v_mfma_f32_16x16x32_bf16 v[2:5], v[200:203], v[232:235], v[2:5]
	s_barrier
	s_add_i32 s12, 0, 0x18000
	s_add_i32 s13, 0, 0x1c000
	v_add_u32_e32 v158, s12, v143
	v_add_u32_e32 v165, s13, v143
	ds_read_b128 v[146:149], v158
	ds_read_b128 v[150:153], v158 offset:1024
	ds_read_b128 v[154:157], v158 offset:2048
	ds_read_b128 v[158:161], v158 offset:3072
	ds_read_b128 v[170:173], v165
	ds_read_b128 v[174:177], v165 offset:1024
	ds_read_b128 v[196:199], v165 offset:2048
	ds_read_b128 v[200:203], v165 offset:3072
	s_add_u32 s92, s92, s20
	s_addc_u32 s93, s93, 0
	s_mov_b32 m0, s30
	v_lshl_add_u64 v[238:239], s[92:93], 0, v[134:135]
	ds_read_b128 v[204:207], v145 offset:32768
	ds_read_b128 v[208:211], v145 offset:33792
	ds_read_b128 v[212:215], v145 offset:34816
	ds_read_b128 v[216:219], v145 offset:35840
	ds_read_b128 v[220:223], v145 offset:36864
	ds_read_b128 v[224:227], v145 offset:37888
	ds_read_b128 v[228:231], v145 offset:38912
	ds_read_b128 v[232:235], v145 offset:39936
	global_load_lds_dwordx4 v[238:239], off
	v_lshl_add_u64 v[238:239], s[92:93], 0, v[132:133]
	s_mov_b32 m0, s31
	s_nop 0
	global_load_lds_dwordx4 v[238:239], off
	s_waitcnt vmcnt(8)
	s_waitcnt lgkmcnt(0)
	s_barrier
; #define PG8_STAGE(bufoff, gbase, voff) do { _Pragma("unroll") for (int _i = 0; _i < 2; ++_i) \
;         __builtin_amdgcn_global_load_lds((const unsigned*)((const char*)(gbase) + (voff)[_i]), (LAS unsigned*)(lds + (bufoff) + ldsw + _i * 8192), 16, 0, 0); } while (0)
; #define PG8_LDA(dst, b, h) do { _Pragma("unroll") for (int m = 0; m < 4; ++m) _Pragma("unroll") for (int k = 0; k < 2; ++k) dst[m][k] = *(const LAS bf16x8*)(lds + PG8_SA(b, h) + aoff + m * 2048 + k * 1024); } while (0)
; #define PG8_MMA(ai, bj, At, Bt) do { __builtin_amdgcn_s_setprio(1); _Pragma("unroll") for (int m = 0; m < 4; ++m) _Pragma("unroll") for (int n = 0; n < 2; ++n) _Pragma("unroll") for (int k = 0; k < 2; ++k) \
;         acc[ai][bj][m][n] = __builtin_amdgcn_mfma_f32_16x16x32_bf16(Bt[n][k], At[m][k], acc[ai][bj][m][n], 0, 0, 0); __builtin_amdgcn_s_setprio(0); } while (0)
; #define PG8_WAIT_V(n) asm volatile("s_waitcnt vmcnt(" #n ")" ::: "memory")
; #define PG8_WAIT_L(n) asm volatile("s_waitcnt lgkmcnt(" #n ")" ::: "memory")
; #define PG8_BAR __builtin_amdgcn_s_barrier()
; #define PG8_SCHED __builtin_amdgcn_sched_barrier(0)
; template <class Epi>
; DI void gemm_phase(LAS unsigned char* lds, int tid, const Gemm g, const Order& S, const Epi& E) {
;     ...
;             PG8_WAIT_V(8); PG8_WAIT_L(0); PG8_BAR; PG8_MMA(0, 0, At, B0); PG8_MMA(0, 1, At, B1); PG8_BAR; PG8_SCHED;
;             PG8_LDA(At, 1, 1); PG8_STAGE(PG8_SB(1, 0), b3, voffB); PG8_STAGE(PG8_SB(1, 1), b3 + hstepB, voffB); PG8_STAGE(PG8_SA(1, 0), a3, voffA);
;             PG8_WAIT_V(8); PG8_WAIT_L(0); PG8_BAR; PG8_MMA(1, 0, At, B0); PG8_MMA(1, 1, At, B1); PG8_BAR; PG8_SCHED;
;         }
;         if (wr == 0) PG8_BAR;
	s_waitcnt lgkmcnt(0)
	v_mfma_f32_16x16x32_bf16 v[126:129], v[146:149], v[204:207], v[126:129]
	v_mfma_f32_16x16x32_bf16 v[122:125], v[154:157], v[204:207], v[122:125]
	v_mfma_f32_16x16x32_bf16 v[118:121], v[146:149], v[212:215], v[118:121]
	v_mfma_f32_16x16x32_bf16 v[110:113], v[154:157], v[212:215], v[110:113]
	v_mfma_f32_16x16x32_bf16 v[102:105], v[146:149], v[220:223], v[102:105]
	v_mfma_f32_16x16x32_bf16 v[94:97], v[154:157], v[220:223], v[94:97]
	v_mfma_f32_16x16x32_bf16 v[86:89], v[146:149], v[228:231], v[86:89]
	v_mfma_f32_16x16x32_bf16 v[78:81], v[154:157], v[228:231], v[78:81]
	v_mfma_f32_16x16x32_bf16 v[126:129], v[150:153], v[208:211], v[126:129]
	v_mfma_f32_16x16x32_bf16 v[122:125], v[158:161], v[208:211], v[122:125]
	v_mfma_f32_16x16x32_bf16 v[118:121], v[150:153], v[216:219], v[118:121]
	v_mfma_f32_16x16x32_bf16 v[110:113], v[158:161], v[216:219], v[110:113]
	v_mfma_f32_16x16x32_bf16 v[102:105], v[150:153], v[224:227], v[102:105]
	v_mfma_f32_16x16x32_bf16 v[94:97], v[158:161], v[224:227], v[94:97]
	v_mfma_f32_16x16x32_bf16 v[86:89], v[150:153], v[232:235], v[86:89]
	v_mfma_f32_16x16x32_bf16 v[78:81], v[158:161], v[232:235], v[78:81]
	v_mfma_f32_16x16x32_bf16 v[114:117], v[170:173], v[204:207], v[114:117]
	v_mfma_f32_16x16x32_bf16 v[106:109], v[196:199], v[204:207], v[106:109]
	v_mfma_f32_16x16x32_bf16 v[98:101], v[170:173], v[212:215], v[98:101]
	v_mfma_f32_16x16x32_bf16 v[90:93], v[196:199], v[212:215], v[90:93]
	v_mfma_f32_16x16x32_bf16 v[82:85], v[170:173], v[220:223], v[82:85]
	v_mfma_f32_16x16x32_bf16 v[74:77], v[196:199], v[220:223], v[74:77]
	v_mfma_f32_16x16x32_bf16 v[70:73], v[170:173], v[228:231], v[70:73]
	v_mfma_f32_16x16x32_bf16 v[66:69], v[196:199], v[228:231], v[66:69]
	v_mfma_f32_16x16x32_bf16 v[114:117], v[174:177], v[208:211], v[114:117]
	v_mfma_f32_16x16x32_bf16 v[106:109], v[200:203], v[208:211], v[106:109]
	v_mfma_f32_16x16x32_bf16 v[98:101], v[174:177], v[216:219], v[98:101]
	v_mfma_f32_16x16x32_bf16 v[90:93], v[200:203], v[216:219], v[90:93]
	v_mfma_f32_16x16x32_bf16 v[82:85], v[174:177], v[224:227], v[82:85]
	v_mfma_f32_16x16x32_bf16 v[74:77], v[200:203], v[224:227], v[74:77]
	v_mfma_f32_16x16x32_bf16 v[70:73], v[174:177], v[232:235], v[70:73]
	v_mfma_f32_16x16x32_bf16 v[66:69], v[200:203], v[232:235], v[66:69]
	s_barrier
	s_add_i32 s12, s12, s17
	v_lshl_add_u64 v[140:141], v[140:141], 0, s[24:25]
	s_mov_b32 m0, s12
	ds_read_b128 v[204:207], v145 offset:49152
	ds_read_b128 v[208:211], v145 offset:50176
	ds_read_b128 v[212:215], v145 offset:51200
	ds_read_b128 v[216:219], v145 offset:52224
	ds_read_b128 v[220:223], v145 offset:53248
	ds_read_b128 v[224:227], v145 offset:54272
	ds_read_b128 v[228:231], v145 offset:55296
	ds_read_b128 v[232:235], v145 offset:56320
	global_load_lds_dwordx4 v[140:141], off
	v_lshl_add_u64 v[140:141], v[166:167], 0, s[24:25]
	s_add_i32 m0, s12, 0x2000
	s_add_i32 s12, s13, s17
	global_load_lds_dwordx4 v[140:141], off
	v_lshl_add_u64 v[140:141], v[178:179], 0, s[24:25]
	s_mov_b32 m0, s12
	s_nop 0
	global_load_lds_dwordx4 v[140:141], off
	v_lshl_add_u64 v[140:141], v[188:189], 0, s[24:25]
	s_add_i32 m0, s12, 0x2000
	s_nop 0
	global_load_lds_dwordx4 v[140:141], off
	v_lshl_add_u64 v[140:141], v[190:191], 0, s[24:25]
	s_mov_b32 m0, s40
	s_nop 0
	global_load_lds_dwordx4 v[140:141], off
	v_lshl_add_u64 v[140:141], v[236:237], 0, s[24:25]
	s_mov_b32 m0, s41
	s_nop 0
	global_load_lds_dwordx4 v[140:141], off
	s_waitcnt vmcnt(8)
	s_waitcnt lgkmcnt(0)
	s_barrier
	s_waitcnt lgkmcnt(0)
	v_mfma_f32_16x16x32_bf16 v[62:65], v[146:149], v[204:207], v[62:65]
	v_mfma_f32_16x16x32_bf16 v[58:61], v[154:157], v[204:207], v[58:61]
	v_mfma_f32_16x16x32_bf16 v[54:57], v[146:149], v[212:215], v[54:57]
	v_mfma_f32_16x16x32_bf16 v[46:49], v[154:157], v[212:215], v[46:49]
	v_mfma_f32_16x16x32_bf16 v[38:41], v[146:149], v[220:223], v[38:41]
	v_mfma_f32_16x16x32_bf16 v[30:33], v[154:157], v[220:223], v[30:33]
	v_mfma_f32_16x16x32_bf16 v[22:25], v[146:149], v[228:231], v[22:25]
	v_mfma_f32_16x16x32_bf16 v[14:17], v[154:157], v[228:231], v[14:17]
	v_mfma_f32_16x16x32_bf16 v[62:65], v[150:153], v[208:211], v[62:65]
	v_mfma_f32_16x16x32_bf16 v[58:61], v[158:161], v[208:211], v[58:61]
	v_mfma_f32_16x16x32_bf16 v[54:57], v[150:153], v[216:219], v[54:57]
	v_mfma_f32_16x16x32_bf16 v[46:49], v[158:161], v[216:219], v[46:49]
	v_mfma_f32_16x16x32_bf16 v[38:41], v[150:153], v[224:227], v[38:41]
	v_mfma_f32_16x16x32_bf16 v[30:33], v[158:161], v[224:227], v[30:33]
	v_mfma_f32_16x16x32_bf16 v[22:25], v[150:153], v[232:235], v[22:25]
	v_mfma_f32_16x16x32_bf16 v[14:17], v[158:161], v[232:235], v[14:17]
	v_mfma_f32_16x16x32_bf16 v[50:53], v[170:173], v[204:207], v[50:53]
	v_mfma_f32_16x16x32_bf16 v[42:45], v[196:199], v[204:207], v[42:45]
	v_mfma_f32_16x16x32_bf16 v[34:37], v[170:173], v[212:215], v[34:37]
	v_mfma_f32_16x16x32_bf16 v[26:29], v[196:199], v[212:215], v[26:29]
	v_mfma_f32_16x16x32_bf16 v[18:21], v[170:173], v[220:223], v[18:21]
	v_mfma_f32_16x16x32_bf16 v[10:13], v[196:199], v[220:223], v[10:13]
	v_mfma_f32_16x16x32_bf16 v[6:9], v[170:173], v[228:231], v[6:9]
	v_mfma_f32_16x16x32_bf16 v[2:5], v[196:199], v[228:231], v[2:5]
	v_mfma_f32_16x16x32_bf16 v[50:53], v[174:177], v[208:211], v[50:53]
	v_mfma_f32_16x16x32_bf16 v[42:45], v[200:203], v[208:211], v[42:45]
	v_mfma_f32_16x16x32_bf16 v[34:37], v[174:177], v[216:219], v[34:37]
	v_mfma_f32_16x16x32_bf16 v[26:29], v[200:203], v[216:219], v[26:29]
	v_mfma_f32_16x16x32_bf16 v[18:21], v[174:177], v[224:227], v[18:21]
	v_mfma_f32_16x16x32_bf16 v[10:13], v[200:203], v[224:227], v[10:13]
	v_mfma_f32_16x16x32_bf16 v[6:9], v[174:177], v[232:235], v[6:9]
	v_mfma_f32_16x16x32_bf16 v[2:5], v[200:203], v[232:235], v[2:5]
	s_barrier
	s_add_u32 s90, s90, 0x100
	s_addc_u32 s91, s91, 0
	s_add_u32 s53, s53, 0x100
	s_addc_u32 vcc_lo, vcc_lo, 0
	s_cmp_ge_u32 vcc_hi, s37
	s_mov_b32 s92, vcc_hi
	s_cbranch_scc0 .LBB0_466
	s_and_b64 vcc, exec, s[86:87]
	s_cbranch_vccz .LBB0_469
	s_barrier

; DI const char* a_of(const Gemm& g, const Unit& u) { return (const char*)(g.A + (size_t)u.pz * g.zA + (size_t)u.pm * BM * g.lda); }
; DI const char* b_of(const Gemm& g, const Unit& u) { return (const char*)(g.Bt + (size_t)u.pz * g.zB + (size_t)u.pn * BM * g.ldb); }
; #define PG8_STAGE(bufoff, gbase, voff) do { _Pragma("unroll") for (int _i = 0; _i < 2; ++_i) \
;         __builtin_amdgcn_global_load_lds((const unsigned*)((const char*)(gbase) + (voff)[_i]), (LAS unsigned*)(lds + (bufoff) + ldsw + _i * 8192), 16, 0, 0); } while (0)
; #define PG8_LDA(dst, b, h) do { _Pragma("unroll") for (int m = 0; m < 4; ++m) _Pragma("unroll") for (int k = 0; k < 2; ++k) dst[m][k] = *(const LAS bf16x8*)(lds + PG8_SA(b, h) + aoff + m * 2048 + k * 1024); } while (0)
; #define PG8_LDB(dst, b, h) do { _Pragma("unroll") for (int n = 0; n < 2; ++n) _Pragma("unroll") for (int k = 0; k < 2; ++k) dst[n][k] = *(const LAS bf16x8*)(lds + PG8_SB(b, h) + boff + n * 2048 + k * 1024); } while (0)
; #define PG8_WAIT_V(n) asm volatile("s_waitcnt vmcnt(" #n ")" ::: "memory")
; #define PG8_WAIT_L(n) asm volatile("s_waitcnt lgkmcnt(" #n ")" ::: "memory")
; template <class Epi>
; DI void gemm_phase(LAS unsigned char* lds, int tid, const Gemm g, const Order& S, const Epi& E) {
;     ...
;         const bool has_next = S.next(ui + 1, nxt);
;         const char* nA = has_next ? a_of(g, nxt) : cA; const char* nB = has_next ? b_of(g, nxt) : cB;
; #pragma unroll 1
;         for (int t = 0; t < nt; t += 2) {
;             const bool last = (t == nt - 2);
;             const char* a1 = cA + (size_t)(t + 1) * kstep;
;             const char* a2 = last ? nA : cA + (size_t)(t + 2) * kstep; const char* b2 = last ? nB : cB + (size_t)(t + 2) * kstep;
;             const char* a3 = a2 + kstep; const char* b3 = b2 + kstep;
;             PG8_LDB(B0, 0, 0); PG8_LDB(B1, 0, 1); PG8_SCHED; PG8_LDA(At, 0, 0); PG8_STAGE(PG8_SA(1, 1), a1 + hstepA, voffA);
;             PG8_WAIT_V(8); PG8_WAIT_L(0); PG8_BAR; PG8_MMA(0, 0, At, B0); PG8_MMA(0, 1, At, B1); PG8_BAR; PG8_SCHED;
;     ...
; #pragma unroll
;         for (int a = 0; a < 2; ++a)
; #pragma unroll
;             for (int b = 0; b < 2; ++b)
; #pragma unroll
;                 for (int m = 0; m < 4; ++m)
; #pragma unroll
;                     for (int n = 0; n < 2; ++n) acc[a][b][m][n] = (f32x4){0.f, 0.f, 0.f, 0.f};
;         cur = nxt; cA = nA; cB = nB; ++ui;
.LBB0_492:
	s_add_u32 s84, s84, 0x80
	s_addc_u32 s85, s85, 0
	s_add_u32 s30, s86, 0x100
	v_mov_b32_e32 v2, 0
	s_addc_u32 s31, s87, 0
	s_mov_b32 s33, 0
	v_mov_b32_e32 v3, v2
	v_mov_b64_e32 v[4:5], v[2:3]
	v_mov_b64_e32 v[6:7], v[2:3]
	v_mov_b64_e32 v[8:9], v[2:3]
	v_mov_b64_e32 v[10:11], v[2:3]
	v_mov_b64_e32 v[12:13], v[2:3]
	v_mov_b64_e32 v[14:15], v[2:3]
	v_mov_b64_e32 v[16:17], v[2:3]
	v_mov_b64_e32 v[18:19], v[2:3]
	v_mov_b64_e32 v[20:21], v[2:3]
	v_mov_b64_e32 v[22:23], v[2:3]
	v_mov_b64_e32 v[24:25], v[2:3]
	v_mov_b64_e32 v[26:27], v[2:3]
	v_mov_b64_e32 v[28:29], v[2:3]
	v_mov_b64_e32 v[30:31], v[2:3]
	v_mov_b64_e32 v[32:33], v[2:3]
	v_mov_b64_e32 v[34:35], v[2:3]
	v_mov_b64_e32 v[36:37], v[2:3]
	v_mov_b64_e32 v[38:39], v[2:3]
	v_mov_b64_e32 v[40:41], v[2:3]
	v_mov_b64_e32 v[42:43], v[2:3]
	v_mov_b64_e32 v[44:45], v[2:3]
	v_mov_b64_e32 v[46:47], v[2:3]
	v_mov_b64_e32 v[48:49], v[2:3]
	v_mov_b64_e32 v[50:51], v[2:3]
	v_mov_b64_e32 v[52:53], v[2:3]
	v_mov_b64_e32 v[54:55], v[2:3]
	v_mov_b64_e32 v[56:57], v[2:3]
	v_mov_b64_e32 v[58:59], v[2:3]
	v_mov_b64_e32 v[60:61], v[2:3]
	v_mov_b64_e32 v[62:63], v[2:3]
	v_mov_b64_e32 v[64:65], v[2:3]
	v_mov_b64_e32 v[66:67], v[2:3]
	v_mov_b64_e32 v[68:69], v[2:3]
	v_mov_b64_e32 v[70:71], v[2:3]
	v_mov_b64_e32 v[72:73], v[2:3]
	v_mov_b64_e32 v[74:75], v[2:3]
	v_mov_b64_e32 v[76:77], v[2:3]
	v_mov_b64_e32 v[78:79], v[2:3]
	v_mov_b64_e32 v[80:81], v[2:3]
	v_mov_b64_e32 v[82:83], v[2:3]
	v_mov_b64_e32 v[84:85], v[2:3]
	v_mov_b64_e32 v[86:87], v[2:3]
	v_mov_b64_e32 v[88:89], v[2:3]
	v_mov_b64_e32 v[90:91], v[2:3]
	v_mov_b64_e32 v[92:93], v[2:3]
	v_mov_b64_e32 v[94:95], v[2:3]
	v_mov_b64_e32 v[96:97], v[2:3]
	v_mov_b64_e32 v[98:99], v[2:3]
	v_mov_b64_e32 v[100:101], v[2:3]
	v_mov_b64_e32 v[102:103], v[2:3]
	v_mov_b64_e32 v[104:105], v[2:3]
	v_mov_b64_e32 v[106:107], v[2:3]
	v_mov_b64_e32 v[108:109], v[2:3]
	v_mov_b64_e32 v[110:111], v[2:3]
	v_mov_b64_e32 v[112:113], v[2:3]
	v_mov_b64_e32 v[114:115], v[2:3]
	v_mov_b64_e32 v[116:117], v[2:3]
	v_mov_b64_e32 v[118:119], v[2:3]
	v_mov_b64_e32 v[120:121], v[2:3]
	v_mov_b64_e32 v[122:123], v[2:3]
	v_mov_b64_e32 v[124:125], v[2:3]
	v_mov_b64_e32 v[126:127], v[2:3]
	v_mov_b64_e32 v[128:129], v[2:3]
	v_readfirstlane_b32 s99, v164
	s_nop 0
	s_cmp_lt_u32 s99, 0x100
	s_cbranch_scc1 .Lprio_493
	s_setprio 1
.Lprio_493:
.LBB0_493:
	s_add_i32 s40, s33, 2
	s_add_u32 s41, s84, 0x80
	s_addc_u32 s45, s85, 0
	s_add_i32 s47, 0, 0x10000
	s_cmp_eq_u32 s36, s33
	s_cselect_b32 s87, s7, s45
	s_cselect_b32 s86, s6, s41
	s_cselect_b32 s53, s83, s31
	s_cselect_b32 s52, s82, s30
	s_add_i32 s33, 0, 0x14000
	v_add_u32_e32 v152, s47, v168
	v_add_u32_e32 v160, s33, v168
	ds_read_b128 v[140:143], v152
	ds_read_b128 v[144:147], v152 offset:1024
	ds_read_b128 v[148:151], v152 offset:2048
	ds_read_b128 v[152:155], v152 offset:3072
	ds_read_b128 v[156:159], v160
	ds_read_b128 v[172:175], v160 offset:1024
	ds_read_b128 v[176:179], v160 offset:2048
	ds_read_b128 v[196:199], v160 offset:3072
	v_lshl_add_u64 v[160:161], s[84:85], 0, v[136:137]
	s_add_i32 m0, s46, 0xc000
	ds_read_b128 v[200:203], v171
	ds_read_b128 v[204:207], v171 offset:1024
	ds_read_b128 v[208:211], v171 offset:2048
	ds_read_b128 v[212:215], v171 offset:3072
	ds_read_b128 v[216:219], v171 offset:4096
	ds_read_b128 v[220:223], v171 offset:5120
	ds_read_b128 v[224:227], v171 offset:6144
	ds_read_b128 v[228:231], v171 offset:7168
	global_load_lds_dwordx4 v[160:161], off
	v_lshl_add_u64 v[160:161], s[84:85], 0, v[138:139]
	s_add_i32 m0, s46, 0xe000
	s_nop 0
	global_load_lds_dwordx4 v[160:161], off
	s_waitcnt vmcnt(8)
	s_waitcnt lgkmcnt(0)
	s_barrier
	s_waitcnt lgkmcnt(0)
	v_mfma_f32_16x16x32_bf16 v[126:129], v[140:143], v[200:203], v[126:129]
	v_mfma_f32_16x16x32_bf16 v[122:125], v[148:151], v[200:203], v[122:125]
	v_mfma_f32_16x16x32_bf16 v[118:121], v[140:143], v[208:211], v[118:121]
	v_mfma_f32_16x16x32_bf16 v[114:117], v[148:151], v[208:211], v[114:117]
	v_mfma_f32_16x16x32_bf16 v[94:97], v[140:143], v[216:219], v[94:97]
	v_mfma_f32_16x16x32_bf16 v[90:93], v[148:151], v[216:219], v[90:93]
	v_mfma_f32_16x16x32_bf16 v[86:89], v[140:143], v[224:227], v[86:89]
	v_mfma_f32_16x16x32_bf16 v[82:85], v[148:151], v[224:227], v[82:85]
	v_mfma_f32_16x16x32_bf16 v[126:129], v[144:147], v[204:207], v[126:129]
	v_mfma_f32_16x16x32_bf16 v[122:125], v[152:155], v[204:207], v[122:125]
	v_mfma_f32_16x16x32_bf16 v[118:121], v[144:147], v[212:215], v[118:121]
	v_mfma_f32_16x16x32_bf16 v[114:117], v[152:155], v[212:215], v[114:117]
	v_mfma_f32_16x16x32_bf16 v[94:97], v[144:147], v[220:223], v[94:97]
	v_mfma_f32_16x16x32_bf16 v[90:93], v[152:155], v[220:223], v[90:93]
	v_mfma_f32_16x16x32_bf16 v[86:89], v[144:147], v[228:231], v[86:89]
	v_mfma_f32_16x16x32_bf16 v[82:85], v[152:155], v[228:231], v[82:85]
	v_mfma_f32_16x16x32_bf16 v[110:113], v[156:159], v[200:203], v[110:113]
	v_mfma_f32_16x16x32_bf16 v[106:109], v[176:179], v[200:203], v[106:109]
	v_mfma_f32_16x16x32_bf16 v[102:105], v[156:159], v[208:211], v[102:105]
	v_mfma_f32_16x16x32_bf16 v[98:101], v[176:179], v[208:211], v[98:101]
	v_mfma_f32_16x16x32_bf16 v[78:81], v[156:159], v[216:219], v[78:81]
	v_mfma_f32_16x16x32_bf16 v[74:77], v[176:179], v[216:219], v[74:77]
	v_mfma_f32_16x16x32_bf16 v[70:73], v[156:159], v[224:227], v[70:73]
	v_mfma_f32_16x16x32_bf16 v[66:69], v[176:179], v[224:227], v[66:69]
	v_mfma_f32_16x16x32_bf16 v[110:113], v[172:175], v[204:207], v[110:113]
	v_mfma_f32_16x16x32_bf16 v[106:109], v[196:199], v[204:207], v[106:109]
	v_mfma_f32_16x16x32_bf16 v[102:105], v[172:175], v[212:215], v[102:105]
	v_mfma_f32_16x16x32_bf16 v[98:101], v[196:199], v[212:215], v[98:101]
	v_mfma_f32_16x16x32_bf16 v[78:81], v[172:175], v[220:223], v[78:81]
	v_mfma_f32_16x16x32_bf16 v[74:77], v[196:199], v[220:223], v[74:77]
	v_mfma_f32_16x16x32_bf16 v[70:73], v[172:175], v[228:231], v[70:73]
	v_mfma_f32_16x16x32_bf16 v[66:69], v[196:199], v[228:231], v[66:69]
	s_barrier
; #define PG8_STAGE(bufoff, gbase, voff) do { _Pragma("unroll") for (int _i = 0; _i < 2; ++_i) \
;         __builtin_amdgcn_global_load_lds((const unsigned*)((const char*)(gbase) + (voff)[_i]), (LAS unsigned*)(lds + (bufoff) + ldsw + _i * 8192), 16, 0, 0); } while (0)
; #define PG8_LDA(dst, b, h) do { _Pragma("unroll") for (int m = 0; m < 4; ++m) _Pragma("unroll") for (int k = 0; k < 2; ++k) dst[m][k] = *(const LAS bf16x8*)(lds + PG8_SA(b, h) + aoff + m * 2048 + k * 1024); } while (0)
; #define PG8_LDB(dst, b, h) do { _Pragma("unroll") for (int n = 0; n < 2; ++n) _Pragma("unroll") for (int k = 0; k < 2; ++k) dst[n][k] = *(const LAS bf16x8*)(lds + PG8_SB(b, h) + boff + n * 2048 + k * 1024); } while (0)
; #define PG8_MMA(ai, bj, At, Bt) do { __builtin_amdgcn_s_setprio(1); _Pragma("unroll") for (int m = 0; m < 4; ++m) _Pragma("unroll") for (int n = 0; n < 2; ++n) _Pragma("unroll") for (int k = 0; k < 2; ++k) \
;         acc[ai][bj][m][n] = __builtin_amdgcn_mfma_f32_16x16x32_bf16(Bt[n][k], At[m][k], acc[ai][bj][m][n], 0, 0, 0); __builtin_amdgcn_s_setprio(0); } while (0)
; #define PG8_WAIT_V(n) asm volatile("s_waitcnt vmcnt(" #n ")" ::: "memory")
; #define PG8_WAIT_L(n) asm volatile("s_waitcnt lgkmcnt(" #n ")" ::: "memory")
; #define PG8_BAR __builtin_amdgcn_s_barrier()
; #define PG8_SCHED __builtin_amdgcn_sched_barrier(0)
; template <class Epi>
; DI void gemm_phase(LAS unsigned char* lds, int tid, const Gemm g, const Order& S, const Epi& E) {
;     ...
;             PG8_LDA(At, 0, 1); PG8_STAGE(PG8_SB(0, 0), b2, voffB); PG8_STAGE(PG8_SB(0, 1), b2 + hstepB, voffB); PG8_STAGE(PG8_SA(0, 0), a2, voffA);
;             PG8_WAIT_V(8); PG8_WAIT_L(0); PG8_BAR; PG8_MMA(1, 0, At, B0); PG8_MMA(1, 1, At, B1); PG8_BAR; PG8_SCHED;
;             PG8_LDB(B0, 1, 0); PG8_LDB(B1, 1, 1); PG8_SCHED; PG8_LDA(At, 1, 0); PG8_STAGE(PG8_SA(0, 1), a2 + hstepA, voffA);
;             PG8_WAIT_V(8); PG8_WAIT_L(0); PG8_BAR; PG8_MMA(0, 0, At, B0); PG8_MMA(0, 1, At, B1); PG8_BAR; PG8_SCHED;
	s_add_i32 s41, s47, s10
	v_lshl_add_u64 v[160:161], s[52:53], 0, v[0:1]
	s_mov_b32 m0, s41
	ds_read_b128 v[200:203], v171 offset:16384
	ds_read_b128 v[204:207], v171 offset:17408
	ds_read_b128 v[208:211], v171 offset:18432
	ds_read_b128 v[212:215], v171 offset:19456
	ds_read_b128 v[216:219], v171 offset:20480
	ds_read_b128 v[220:223], v171 offset:21504
	ds_read_b128 v[224:227], v171 offset:22528
	ds_read_b128 v[228:231], v171 offset:23552
	global_load_lds_dwordx4 v[160:161], off
	s_add_i32 m0, s41, 0x2000
	v_lshl_add_u64 v[166:167], s[52:53], 0, v[130:131]
	s_add_u32 s52, s52, s20
	s_addc_u32 s53, s53, 0
	s_add_i32 s33, s33, s10
	global_load_lds_dwordx4 v[166:167], off
	v_lshl_add_u64 v[188:189], s[52:53], 0, v[0:1]
	s_mov_b32 m0, s33
	v_lshl_add_u64 v[190:191], s[52:53], 0, v[130:131]
	global_load_lds_dwordx4 v[188:189], off
	s_add_i32 m0, s33, 0x2000
	v_lshl_add_u64 v[232:233], s[86:87], 0, v[134:135]
	global_load_lds_dwordx4 v[190:191], off
	s_mov_b32 m0, s46
	v_lshl_add_u64 v[234:235], s[86:87], 0, v[132:133]
	global_load_lds_dwordx4 v[232:233], off
	s_mov_b32 m0, s49
	s_nop 0
	global_load_lds_dwordx4 v[234:235], off
	s_waitcnt vmcnt(8)
	s_waitcnt lgkmcnt(0)
	s_barrier
	s_waitcnt lgkmcnt(0)
	v_mfma_f32_16x16x32_bf16 v[62:65], v[140:143], v[200:203], v[62:65]
	v_mfma_f32_16x16x32_bf16 v[58:61], v[148:151], v[200:203], v[58:61]
	v_mfma_f32_16x16x32_bf16 v[54:57], v[140:143], v[208:211], v[54:57]
	v_mfma_f32_16x16x32_bf16 v[50:53], v[148:151], v[208:211], v[50:53]
	v_mfma_f32_16x16x32_bf16 v[30:33], v[140:143], v[216:219], v[30:33]
	v_mfma_f32_16x16x32_bf16 v[26:29], v[148:151], v[216:219], v[26:29]
	v_mfma_f32_16x16x32_bf16 v[22:25], v[140:143], v[224:227], v[22:25]
	v_mfma_f32_16x16x32_bf16 v[18:21], v[148:151], v[224:227], v[18:21]
	v_mfma_f32_16x16x32_bf16 v[62:65], v[144:147], v[204:207], v[62:65]
	v_mfma_f32_16x16x32_bf16 v[58:61], v[152:155], v[204:207], v[58:61]
	v_mfma_f32_16x16x32_bf16 v[54:57], v[144:147], v[212:215], v[54:57]
	v_mfma_f32_16x16x32_bf16 v[50:53], v[152:155], v[212:215], v[50:53]
	v_mfma_f32_16x16x32_bf16 v[30:33], v[144:147], v[220:223], v[30:33]
	v_mfma_f32_16x16x32_bf16 v[26:29], v[152:155], v[220:223], v[26:29]
	v_mfma_f32_16x16x32_bf16 v[22:25], v[144:147], v[228:231], v[22:25]
	v_mfma_f32_16x16x32_bf16 v[18:21], v[152:155], v[228:231], v[18:21]
	v_mfma_f32_16x16x32_bf16 v[46:49], v[156:159], v[200:203], v[46:49]
	v_mfma_f32_16x16x32_bf16 v[42:45], v[176:179], v[200:203], v[42:45]
	v_mfma_f32_16x16x32_bf16 v[38:41], v[156:159], v[208:211], v[38:41]
	v_mfma_f32_16x16x32_bf16 v[34:37], v[176:179], v[208:211], v[34:37]
	v_mfma_f32_16x16x32_bf16 v[14:17], v[156:159], v[216:219], v[14:17]
	v_mfma_f32_16x16x32_bf16 v[10:13], v[176:179], v[216:219], v[10:13]
	v_mfma_f32_16x16x32_bf16 v[6:9], v[156:159], v[224:227], v[6:9]
	v_mfma_f32_16x16x32_bf16 v[2:5], v[176:179], v[224:227], v[2:5]
	v_mfma_f32_16x16x32_bf16 v[46:49], v[172:175], v[204:207], v[46:49]
	v_mfma_f32_16x16x32_bf16 v[42:45], v[196:199], v[204:207], v[42:45]
	v_mfma_f32_16x16x32_bf16 v[38:41], v[172:175], v[212:215], v[38:41]
	v_mfma_f32_16x16x32_bf16 v[34:37], v[196:199], v[212:215], v[34:37]
	v_mfma_f32_16x16x32_bf16 v[14:17], v[172:175], v[220:223], v[14:17]
	v_mfma_f32_16x16x32_bf16 v[10:13], v[196:199], v[220:223], v[10:13]
	v_mfma_f32_16x16x32_bf16 v[6:9], v[172:175], v[228:231], v[6:9]
	v_mfma_f32_16x16x32_bf16 v[2:5], v[196:199], v[228:231], v[2:5]
	s_barrier
	s_add_i32 s33, 0, 0x18000
	s_add_i32 s41, 0, 0x1c000
	v_add_u32_e32 v152, s33, v168
	v_add_u32_e32 v184, s41, v168
	ds_read_b128 v[140:143], v152
	ds_read_b128 v[144:147], v152 offset:1024
	ds_read_b128 v[148:151], v152 offset:2048
	ds_read_b128 v[152:155], v152 offset:3072
	ds_read_b128 v[156:159], v184
	ds_read_b128 v[172:175], v184 offset:1024
	ds_read_b128 v[176:179], v184 offset:2048
	ds_read_b128 v[196:199], v184 offset:3072
	s_add_u32 s52, s86, s20
	s_addc_u32 s53, s87, 0
	s_mov_b32 m0, s92
	v_lshl_add_u64 v[236:237], s[52:53], 0, v[134:135]
	ds_read_b128 v[200:203], v171 offset:32768
	ds_read_b128 v[204:207], v171 offset:33792
	ds_read_b128 v[208:211], v171 offset:34816
	ds_read_b128 v[212:215], v171 offset:35840
	ds_read_b128 v[216:219], v171 offset:36864
	ds_read_b128 v[220:223], v171 offset:37888
	ds_read_b128 v[224:227], v171 offset:38912
	ds_read_b128 v[228:231], v171 offset:39936
	global_load_lds_dwordx4 v[236:237], off
	v_lshl_add_u64 v[236:237], s[52:53], 0, v[132:133]
	s_mov_b32 m0, s93
	s_nop 0
	global_load_lds_dwordx4 v[236:237], off
	s_waitcnt vmcnt(8)
	s_waitcnt lgkmcnt(0)
	s_barrier
; #define PG8_STAGE(bufoff, gbase, voff) do { _Pragma("unroll") for (int _i = 0; _i < 2; ++_i) \
;         __builtin_amdgcn_global_load_lds((const unsigned*)((const char*)(gbase) + (voff)[_i]), (LAS unsigned*)(lds + (bufoff) + ldsw + _i * 8192), 16, 0, 0); } while (0)
; #define PG8_LDA(dst, b, h) do { _Pragma("unroll") for (int m = 0; m < 4; ++m) _Pragma("unroll") for (int k = 0; k < 2; ++k) dst[m][k] = *(const LAS bf16x8*)(lds + PG8_SA(b, h) + aoff + m * 2048 + k * 1024); } while (0)
; #define PG8_MMA(ai, bj, At, Bt) do { __builtin_amdgcn_s_setprio(1); _Pragma("unroll") for (int m = 0; m < 4; ++m) _Pragma("unroll") for (int n = 0; n < 2; ++n) _Pragma("unroll") for (int k = 0; k < 2; ++k) \
;         acc[ai][bj][m][n] = __builtin_amdgcn_mfma_f32_16x16x32_bf16(Bt[n][k], At[m][k], acc[ai][bj][m][n], 0, 0, 0); __builtin_amdgcn_s_setprio(0); } while (0)
; #define PG8_WAIT_V(n) asm volatile("s_waitcnt vmcnt(" #n ")" ::: "memory")
; #define PG8_WAIT_L(n) asm volatile("s_waitcnt lgkmcnt(" #n ")" ::: "memory")
; #define PG8_BAR __builtin_amdgcn_s_barrier()
; #define PG8_SCHED __builtin_amdgcn_sched_barrier(0)
; template <class Epi>
; DI void gemm_phase(LAS unsigned char* lds, int tid, const Gemm g, const Order& S, const Epi& E) {
;     ...
;             PG8_WAIT_V(8); PG8_WAIT_L(0); PG8_BAR; PG8_MMA(0, 0, At, B0); PG8_MMA(0, 1, At, B1); PG8_BAR; PG8_SCHED;
;             PG8_LDA(At, 1, 1); PG8_STAGE(PG8_SB(1, 0), b3, voffB); PG8_STAGE(PG8_SB(1, 1), b3 + hstepB, voffB); PG8_STAGE(PG8_SA(1, 0), a3, voffA);
;             PG8_WAIT_V(8); PG8_WAIT_L(0); PG8_BAR; PG8_MMA(1, 0, At, B0); PG8_MMA(1, 1, At, B1); PG8_BAR; PG8_SCHED;
;         }
;         if (wr == 0) PG8_BAR;
	s_waitcnt lgkmcnt(0)
	v_mfma_f32_16x16x32_bf16 v[126:129], v[140:143], v[200:203], v[126:129]
	v_mfma_f32_16x16x32_bf16 v[122:125], v[148:151], v[200:203], v[122:125]
	v_mfma_f32_16x16x32_bf16 v[118:121], v[140:143], v[208:211], v[118:121]
	v_mfma_f32_16x16x32_bf16 v[114:117], v[148:151], v[208:211], v[114:117]
	v_mfma_f32_16x16x32_bf16 v[94:97], v[140:143], v[216:219], v[94:97]
	v_mfma_f32_16x16x32_bf16 v[90:93], v[148:151], v[216:219], v[90:93]
	v_mfma_f32_16x16x32_bf16 v[86:89], v[140:143], v[224:227], v[86:89]
	v_mfma_f32_16x16x32_bf16 v[82:85], v[148:151], v[224:227], v[82:85]
	v_mfma_f32_16x16x32_bf16 v[126:129], v[144:147], v[204:207], v[126:129]
	v_mfma_f32_16x16x32_bf16 v[122:125], v[152:155], v[204:207], v[122:125]
	v_mfma_f32_16x16x32_bf16 v[118:121], v[144:147], v[212:215], v[118:121]
	v_mfma_f32_16x16x32_bf16 v[114:117], v[152:155], v[212:215], v[114:117]
	v_mfma_f32_16x16x32_bf16 v[94:97], v[144:147], v[220:223], v[94:97]
	v_mfma_f32_16x16x32_bf16 v[90:93], v[152:155], v[220:223], v[90:93]
	v_mfma_f32_16x16x32_bf16 v[86:89], v[144:147], v[228:231], v[86:89]
	v_mfma_f32_16x16x32_bf16 v[82:85], v[152:155], v[228:231], v[82:85]
	v_mfma_f32_16x16x32_bf16 v[110:113], v[156:159], v[200:203], v[110:113]
	v_mfma_f32_16x16x32_bf16 v[106:109], v[176:179], v[200:203], v[106:109]
	v_mfma_f32_16x16x32_bf16 v[102:105], v[156:159], v[208:211], v[102:105]
	v_mfma_f32_16x16x32_bf16 v[98:101], v[176:179], v[208:211], v[98:101]
	v_mfma_f32_16x16x32_bf16 v[78:81], v[156:159], v[216:219], v[78:81]
	v_mfma_f32_16x16x32_bf16 v[74:77], v[176:179], v[216:219], v[74:77]
	v_mfma_f32_16x16x32_bf16 v[70:73], v[156:159], v[224:227], v[70:73]
	v_mfma_f32_16x16x32_bf16 v[66:69], v[176:179], v[224:227], v[66:69]
	v_mfma_f32_16x16x32_bf16 v[110:113], v[172:175], v[204:207], v[110:113]
	v_mfma_f32_16x16x32_bf16 v[106:109], v[196:199], v[204:207], v[106:109]
	v_mfma_f32_16x16x32_bf16 v[102:105], v[172:175], v[212:215], v[102:105]
	v_mfma_f32_16x16x32_bf16 v[98:101], v[196:199], v[212:215], v[98:101]
	v_mfma_f32_16x16x32_bf16 v[78:81], v[172:175], v[220:223], v[78:81]
	v_mfma_f32_16x16x32_bf16 v[74:77], v[196:199], v[220:223], v[74:77]
	v_mfma_f32_16x16x32_bf16 v[70:73], v[172:175], v[228:231], v[70:73]
	v_mfma_f32_16x16x32_bf16 v[66:69], v[196:199], v[228:231], v[66:69]
	s_barrier
	s_add_i32 s33, s33, s10
	v_lshl_add_u64 v[160:161], v[160:161], 0, s[24:25]
	s_mov_b32 m0, s33
	ds_read_b128 v[200:203], v171 offset:49152
	ds_read_b128 v[204:207], v171 offset:50176
	ds_read_b128 v[208:211], v171 offset:51200
	ds_read_b128 v[212:215], v171 offset:52224
	ds_read_b128 v[216:219], v171 offset:53248
	ds_read_b128 v[220:223], v171 offset:54272
	ds_read_b128 v[224:227], v171 offset:55296
	ds_read_b128 v[228:231], v171 offset:56320
	global_load_lds_dwordx4 v[160:161], off
	v_lshl_add_u64 v[160:161], v[166:167], 0, s[24:25]
	s_add_i32 m0, s33, 0x2000
	s_add_i32 s33, s41, s10
	global_load_lds_dwordx4 v[160:161], off
	v_lshl_add_u64 v[160:161], v[188:189], 0, s[24:25]
	s_mov_b32 m0, s33
	s_nop 0
	global_load_lds_dwordx4 v[160:161], off
	v_lshl_add_u64 v[160:161], v[190:191], 0, s[24:25]
	s_add_i32 m0, s33, 0x2000
	s_nop 0
	global_load_lds_dwordx4 v[160:161], off
	v_lshl_add_u64 v[160:161], v[232:233], 0, s[24:25]
	s_mov_b32 m0, s37
	s_nop 0
	global_load_lds_dwordx4 v[160:161], off
	v_lshl_add_u64 v[160:161], v[234:235], 0, s[24:25]
	s_mov_b32 m0, s39
	s_nop 0
	global_load_lds_dwordx4 v[160:161], off
	s_waitcnt vmcnt(8)
	s_waitcnt lgkmcnt(0)
	s_barrier
	s_waitcnt lgkmcnt(0)
	v_mfma_f32_16x16x32_bf16 v[62:65], v[140:143], v[200:203], v[62:65]
	v_mfma_f32_16x16x32_bf16 v[58:61], v[148:151], v[200:203], v[58:61]
	v_mfma_f32_16x16x32_bf16 v[54:57], v[140:143], v[208:211], v[54:57]
	v_mfma_f32_16x16x32_bf16 v[50:53], v[148:151], v[208:211], v[50:53]
	v_mfma_f32_16x16x32_bf16 v[30:33], v[140:143], v[216:219], v[30:33]
	v_mfma_f32_16x16x32_bf16 v[26:29], v[148:151], v[216:219], v[26:29]
	v_mfma_f32_16x16x32_bf16 v[22:25], v[140:143], v[224:227], v[22:25]
	v_mfma_f32_16x16x32_bf16 v[18:21], v[148:151], v[224:227], v[18:21]
	v_mfma_f32_16x16x32_bf16 v[62:65], v[144:147], v[204:207], v[62:65]
	v_mfma_f32_16x16x32_bf16 v[58:61], v[152:155], v[204:207], v[58:61]
	v_mfma_f32_16x16x32_bf16 v[54:57], v[144:147], v[212:215], v[54:57]
	v_mfma_f32_16x16x32_bf16 v[50:53], v[152:155], v[212:215], v[50:53]
	v_mfma_f32_16x16x32_bf16 v[30:33], v[144:147], v[220:223], v[30:33]
	v_mfma_f32_16x16x32_bf16 v[26:29], v[152:155], v[220:223], v[26:29]
	v_mfma_f32_16x16x32_bf16 v[22:25], v[144:147], v[228:231], v[22:25]
	v_mfma_f32_16x16x32_bf16 v[18:21], v[152:155], v[228:231], v[18:21]
	v_mfma_f32_16x16x32_bf16 v[46:49], v[156:159], v[200:203], v[46:49]
	v_mfma_f32_16x16x32_bf16 v[42:45], v[176:179], v[200:203], v[42:45]
	v_mfma_f32_16x16x32_bf16 v[38:41], v[156:159], v[208:211], v[38:41]
	v_mfma_f32_16x16x32_bf16 v[34:37], v[176:179], v[208:211], v[34:37]
	v_mfma_f32_16x16x32_bf16 v[14:17], v[156:159], v[216:219], v[14:17]
	v_mfma_f32_16x16x32_bf16 v[10:13], v[176:179], v[216:219], v[10:13]
	v_mfma_f32_16x16x32_bf16 v[6:9], v[156:159], v[224:227], v[6:9]
	v_mfma_f32_16x16x32_bf16 v[2:5], v[176:179], v[224:227], v[2:5]
	v_mfma_f32_16x16x32_bf16 v[46:49], v[172:175], v[204:207], v[46:49]
	v_mfma_f32_16x16x32_bf16 v[42:45], v[196:199], v[204:207], v[42:45]
	v_mfma_f32_16x16x32_bf16 v[38:41], v[172:175], v[212:215], v[38:41]
	v_mfma_f32_16x16x32_bf16 v[34:37], v[196:199], v[212:215], v[34:37]
	v_mfma_f32_16x16x32_bf16 v[14:17], v[172:175], v[220:223], v[14:17]
	v_mfma_f32_16x16x32_bf16 v[10:13], v[196:199], v[220:223], v[10:13]
	v_mfma_f32_16x16x32_bf16 v[6:9], v[172:175], v[228:231], v[6:9]
	v_mfma_f32_16x16x32_bf16 v[2:5], v[196:199], v[228:231], v[2:5]
	s_barrier
	s_add_u32 s84, s84, 0x100
	s_addc_u32 s85, s85, 0
	s_add_u32 s30, s30, 0x100
	s_addc_u32 s31, s31, 0
	s_cmp_ge_u32 s40, s28
	s_mov_b32 s33, s40
	s_cbranch_scc0 .LBB0_493
	s_and_b64 vcc, exec, s[80:81]
	s_cbranch_vccz .LBB0_496
	s_barrier

; DI const char* a_of(const Gemm& g, const Unit& u) { return (const char*)(g.A + (size_t)u.pz * g.zA + (size_t)u.pm * BM * g.lda); }
; DI const char* b_of(const Gemm& g, const Unit& u) { return (const char*)(g.Bt + (size_t)u.pz * g.zB + (size_t)u.pn * BM * g.ldb); }
; #define PG8_STAGE(bufoff, gbase, voff) do { _Pragma("unroll") for (int _i = 0; _i < 2; ++_i) \
;         __builtin_amdgcn_global_load_lds((const unsigned*)((const char*)(gbase) + (voff)[_i]), (LAS unsigned*)(lds + (bufoff) + ldsw + _i * 8192), 16, 0, 0); } while (0)
; #define PG8_LDA(dst, b, h) do { _Pragma("unroll") for (int m = 0; m < 4; ++m) _Pragma("unroll") for (int k = 0; k < 2; ++k) dst[m][k] = *(const LAS bf16x8*)(lds + PG8_SA(b, h) + aoff + m * 2048 + k * 1024); } while (0)
; #define PG8_LDB(dst, b, h) do { _Pragma("unroll") for (int n = 0; n < 2; ++n) _Pragma("unroll") for (int k = 0; k < 2; ++k) dst[n][k] = *(const LAS bf16x8*)(lds + PG8_SB(b, h) + boff + n * 2048 + k * 1024); } while (0)
; #define PG8_WAIT_V(n) asm volatile("s_waitcnt vmcnt(" #n ")" ::: "memory")
; #define PG8_WAIT_L(n) asm volatile("s_waitcnt lgkmcnt(" #n ")" ::: "memory")
; template <class Epi>
; DI void gemm_phase(LAS unsigned char* lds, int tid, const Gemm g, const Order& S, const Epi& E) {
;     ...
;         const bool has_next = S.next(ui + 1, nxt);
;         const char* nA = has_next ? a_of(g, nxt) : cA; const char* nB = has_next ? b_of(g, nxt) : cB;
; #pragma unroll 1
;         for (int t = 0; t < nt; t += 2) {
;             const bool last = (t == nt - 2);
;             const char* a1 = cA + (size_t)(t + 1) * kstep;
;             const char* a2 = last ? nA : cA + (size_t)(t + 2) * kstep; const char* b2 = last ? nB : cB + (size_t)(t + 2) * kstep;
;             const char* a3 = a2 + kstep; const char* b3 = b2 + kstep;
;             PG8_LDB(B0, 0, 0); PG8_LDB(B1, 0, 1); PG8_SCHED; PG8_LDA(At, 0, 0); PG8_STAGE(PG8_SA(1, 1), a1 + hstepA, voffA);
;             PG8_WAIT_V(8); PG8_WAIT_L(0); PG8_BAR; PG8_MMA(0, 0, At, B0); PG8_MMA(0, 1, At, B1); PG8_BAR; PG8_SCHED;
;     ...
; #pragma unroll
;         for (int a = 0; a < 2; ++a)
; #pragma unroll
;             for (int b = 0; b < 2; ++b)
; #pragma unroll
;                 for (int m = 0; m < 4; ++m)
; #pragma unroll
;                     for (int n = 0; n < 2; ++n) acc[a][b][m][n] = (f32x4){0.f, 0.f, 0.f, 0.f};
;         cur = nxt; cA = nA; cB = nB; ++ui;
.LBB0_512:
	s_ashr_i32 s67, s66, 31
	s_lshl_b64 s[40:41], s[66:67], 19
	s_add_u32 s68, s58, s40
	s_addc_u32 s69, s59, s41
	s_and_b64 s[40:41], s[4:5], exec
	s_cselect_b32 s39, s69, s75
	s_cselect_b32 s40, s68, s74
	s_ashr_i32 s65, s64, 31
	s_lshl_b64 s[46:47], s[64:65], 19
	s_add_u32 s70, s10, s46
	s_addc_u32 s71, s11, s47
	s_and_b64 s[46:47], s[4:5], exec
	s_cselect_b32 s41, s71, s77
	s_cselect_b32 s43, s70, s76
	s_add_u32 s74, s74, 0x40080
	s_addc_u32 s75, s75, 0
	s_add_u32 s45, s76, 0x100
	v_mov_b32_e32 v2, 0
	s_addc_u32 s46, s77, 0
	s_mov_b32 s47, -2
	v_mov_b32_e32 v3, v2
	v_mov_b64_e32 v[4:5], v[2:3]
	v_mov_b64_e32 v[6:7], v[2:3]
	v_mov_b64_e32 v[8:9], v[2:3]
	v_mov_b64_e32 v[10:11], v[2:3]
	v_mov_b64_e32 v[12:13], v[2:3]
	v_mov_b64_e32 v[14:15], v[2:3]
	v_mov_b64_e32 v[16:17], v[2:3]
	v_mov_b64_e32 v[18:19], v[2:3]
	v_mov_b64_e32 v[20:21], v[2:3]
	v_mov_b64_e32 v[22:23], v[2:3]
	v_mov_b64_e32 v[24:25], v[2:3]
	v_mov_b64_e32 v[26:27], v[2:3]
	v_mov_b64_e32 v[28:29], v[2:3]
	v_mov_b64_e32 v[30:31], v[2:3]
	v_mov_b64_e32 v[32:33], v[2:3]
	v_mov_b64_e32 v[34:35], v[2:3]
	v_mov_b64_e32 v[36:37], v[2:3]
	v_mov_b64_e32 v[38:39], v[2:3]
	v_mov_b64_e32 v[40:41], v[2:3]
	v_mov_b64_e32 v[42:43], v[2:3]
	v_mov_b64_e32 v[44:45], v[2:3]
	v_mov_b64_e32 v[46:47], v[2:3]
	v_mov_b64_e32 v[48:49], v[2:3]
	v_mov_b64_e32 v[50:51], v[2:3]
	v_mov_b64_e32 v[52:53], v[2:3]
	v_mov_b64_e32 v[54:55], v[2:3]
	v_mov_b64_e32 v[56:57], v[2:3]
	v_mov_b64_e32 v[58:59], v[2:3]
	v_mov_b64_e32 v[60:61], v[2:3]
	v_mov_b64_e32 v[62:63], v[2:3]
	v_mov_b64_e32 v[64:65], v[2:3]
	v_mov_b64_e32 v[66:67], v[2:3]
	v_mov_b64_e32 v[68:69], v[2:3]
	v_mov_b64_e32 v[70:71], v[2:3]
	v_mov_b64_e32 v[72:73], v[2:3]
	v_mov_b64_e32 v[74:75], v[2:3]
	v_mov_b64_e32 v[76:77], v[2:3]
	v_mov_b64_e32 v[78:79], v[2:3]
	v_mov_b64_e32 v[80:81], v[2:3]
	v_mov_b64_e32 v[82:83], v[2:3]
	v_mov_b64_e32 v[84:85], v[2:3]
	v_mov_b64_e32 v[86:87], v[2:3]
	v_mov_b64_e32 v[88:89], v[2:3]
	v_mov_b64_e32 v[90:91], v[2:3]
	v_mov_b64_e32 v[92:93], v[2:3]
	v_mov_b64_e32 v[94:95], v[2:3]
	v_mov_b64_e32 v[96:97], v[2:3]
	v_mov_b64_e32 v[98:99], v[2:3]
	v_mov_b64_e32 v[100:101], v[2:3]
	v_mov_b64_e32 v[102:103], v[2:3]
	v_mov_b64_e32 v[104:105], v[2:3]
	v_mov_b64_e32 v[106:107], v[2:3]
	v_mov_b64_e32 v[108:109], v[2:3]
	v_mov_b64_e32 v[110:111], v[2:3]
	v_mov_b64_e32 v[112:113], v[2:3]
	v_mov_b64_e32 v[114:115], v[2:3]
	v_mov_b64_e32 v[116:117], v[2:3]
	v_mov_b64_e32 v[118:119], v[2:3]
	v_mov_b64_e32 v[120:121], v[2:3]
	v_mov_b64_e32 v[122:123], v[2:3]
	v_mov_b64_e32 v[124:125], v[2:3]
	v_mov_b64_e32 v[126:127], v[2:3]
	v_mov_b64_e32 v[128:129], v[2:3]
	v_readfirstlane_b32 s99, v164
	s_nop 0
	s_cmp_lt_u32 s99, 0x100
	s_cbranch_scc1 .Lprio_513
	s_setprio 1
.Lprio_513:
.LBB0_513:
	s_add_u32 s48, s74, 0xfffc0080
	s_addc_u32 s49, s75, -1
	s_add_i32 s51, 0, 0x10000
	s_cmp_eq_u32 s47, 12
	s_cselect_b32 s79, s39, s49
	s_cselect_b32 s78, s40, s48
	s_cselect_b32 s77, s41, s46
	s_cselect_b32 s76, s43, s45
	s_add_i32 s52, 0, 0x14000
	v_add_u32_e32 v156, s51, v145
	v_add_u32_e32 v160, s52, v145
	ds_read_b128 v[140:143], v156
	ds_read_b128 v[148:151], v156 offset:1024
	ds_read_b128 v[152:155], v156 offset:2048
	ds_read_b128 v[156:159], v156 offset:3072
	ds_read_b128 v[164:167], v160
	ds_read_b128 v[170:173], v160 offset:1024
	ds_read_b128 v[174:177], v160 offset:2048
	ds_read_b128 v[196:199], v160 offset:3072
	v_lshl_add_u64 v[160:161], s[74:75], 0, v[136:137]
	s_add_i32 m0, s22, 0xc000
	ds_read_b128 v[200:203], v147
	ds_read_b128 v[204:207], v147 offset:1024
	ds_read_b128 v[208:211], v147 offset:2048
	ds_read_b128 v[212:215], v147 offset:3072
	ds_read_b128 v[216:219], v147 offset:4096
	ds_read_b128 v[220:223], v147 offset:5120
	ds_read_b128 v[224:227], v147 offset:6144
	ds_read_b128 v[228:231], v147 offset:7168
	global_load_lds_dwordx4 v[160:161], off
	v_lshl_add_u64 v[160:161], s[74:75], 0, v[138:139]
	s_add_i32 m0, s22, 0xe000
	s_nop 0
	global_load_lds_dwordx4 v[160:161], off
	s_waitcnt vmcnt(8)
	s_waitcnt lgkmcnt(0)
	s_barrier
	s_waitcnt lgkmcnt(0)
	v_mfma_f32_16x16x32_bf16 v[126:129], v[140:143], v[200:203], v[126:129]
	v_mfma_f32_16x16x32_bf16 v[122:125], v[152:155], v[200:203], v[122:125]
	v_mfma_f32_16x16x32_bf16 v[110:113], v[140:143], v[208:211], v[110:113]
	v_mfma_f32_16x16x32_bf16 v[106:109], v[152:155], v[208:211], v[106:109]
	v_mfma_f32_16x16x32_bf16 v[94:97], v[140:143], v[216:219], v[94:97]
	v_mfma_f32_16x16x32_bf16 v[90:93], v[152:155], v[216:219], v[90:93]
	v_mfma_f32_16x16x32_bf16 v[78:81], v[140:143], v[224:227], v[78:81]
	v_mfma_f32_16x16x32_bf16 v[74:77], v[152:155], v[224:227], v[74:77]
	v_mfma_f32_16x16x32_bf16 v[126:129], v[148:151], v[204:207], v[126:129]
	v_mfma_f32_16x16x32_bf16 v[122:125], v[156:159], v[204:207], v[122:125]
	v_mfma_f32_16x16x32_bf16 v[110:113], v[148:151], v[212:215], v[110:113]
	v_mfma_f32_16x16x32_bf16 v[106:109], v[156:159], v[212:215], v[106:109]
	v_mfma_f32_16x16x32_bf16 v[94:97], v[148:151], v[220:223], v[94:97]
	v_mfma_f32_16x16x32_bf16 v[90:93], v[156:159], v[220:223], v[90:93]
	v_mfma_f32_16x16x32_bf16 v[78:81], v[148:151], v[228:231], v[78:81]
	v_mfma_f32_16x16x32_bf16 v[74:77], v[156:159], v[228:231], v[74:77]
	v_mfma_f32_16x16x32_bf16 v[118:121], v[164:167], v[200:203], v[118:121]
	v_mfma_f32_16x16x32_bf16 v[114:117], v[174:177], v[200:203], v[114:117]
	v_mfma_f32_16x16x32_bf16 v[102:105], v[164:167], v[208:211], v[102:105]
	v_mfma_f32_16x16x32_bf16 v[98:101], v[174:177], v[208:211], v[98:101]
	v_mfma_f32_16x16x32_bf16 v[86:89], v[164:167], v[216:219], v[86:89]
	v_mfma_f32_16x16x32_bf16 v[82:85], v[174:177], v[216:219], v[82:85]
	v_mfma_f32_16x16x32_bf16 v[70:73], v[164:167], v[224:227], v[70:73]
	v_mfma_f32_16x16x32_bf16 v[66:69], v[174:177], v[224:227], v[66:69]
	v_mfma_f32_16x16x32_bf16 v[118:121], v[170:173], v[204:207], v[118:121]
	v_mfma_f32_16x16x32_bf16 v[114:117], v[196:199], v[204:207], v[114:117]
	v_mfma_f32_16x16x32_bf16 v[102:105], v[170:173], v[212:215], v[102:105]
	v_mfma_f32_16x16x32_bf16 v[98:101], v[196:199], v[212:215], v[98:101]
	v_mfma_f32_16x16x32_bf16 v[86:89], v[170:173], v[220:223], v[86:89]
	v_mfma_f32_16x16x32_bf16 v[82:85], v[196:199], v[220:223], v[82:85]
	v_mfma_f32_16x16x32_bf16 v[70:73], v[170:173], v[228:231], v[70:73]
	v_mfma_f32_16x16x32_bf16 v[66:69], v[196:199], v[228:231], v[66:69]
	s_barrier
; #define PG8_STAGE(bufoff, gbase, voff) do { _Pragma("unroll") for (int _i = 0; _i < 2; ++_i) \
;         __builtin_amdgcn_global_load_lds((const unsigned*)((const char*)(gbase) + (voff)[_i]), (LAS unsigned*)(lds + (bufoff) + ldsw + _i * 8192), 16, 0, 0); } while (0)
; #define PG8_LDA(dst, b, h) do { _Pragma("unroll") for (int m = 0; m < 4; ++m) _Pragma("unroll") for (int k = 0; k < 2; ++k) dst[m][k] = *(const LAS bf16x8*)(lds + PG8_SA(b, h) + aoff + m * 2048 + k * 1024); } while (0)
; #define PG8_LDB(dst, b, h) do { _Pragma("unroll") for (int n = 0; n < 2; ++n) _Pragma("unroll") for (int k = 0; k < 2; ++k) dst[n][k] = *(const LAS bf16x8*)(lds + PG8_SB(b, h) + boff + n * 2048 + k * 1024); } while (0)
; #define PG8_MMA(ai, bj, At, Bt) do { __builtin_amdgcn_s_setprio(1); _Pragma("unroll") for (int m = 0; m < 4; ++m) _Pragma("unroll") for (int n = 0; n < 2; ++n) _Pragma("unroll") for (int k = 0; k < 2; ++k) \
;         acc[ai][bj][m][n] = __builtin_amdgcn_mfma_f32_16x16x32_bf16(Bt[n][k], At[m][k], acc[ai][bj][m][n], 0, 0, 0); __builtin_amdgcn_s_setprio(0); } while (0)
; #define PG8_WAIT_V(n) asm volatile("s_waitcnt vmcnt(" #n ")" ::: "memory")
; #define PG8_WAIT_L(n) asm volatile("s_waitcnt lgkmcnt(" #n ")" ::: "memory")
; #define PG8_BAR __builtin_amdgcn_s_barrier()
; #define PG8_SCHED __builtin_amdgcn_sched_barrier(0)
; template <class Epi>
; DI void gemm_phase(LAS unsigned char* lds, int tid, const Gemm g, const Order& S, const Epi& E) {
;     ...
;             PG8_LDA(At, 0, 1); PG8_STAGE(PG8_SB(0, 0), b2, voffB); PG8_STAGE(PG8_SB(0, 1), b2 + hstepB, voffB); PG8_STAGE(PG8_SA(0, 0), a2, voffA);
;             PG8_WAIT_V(8); PG8_WAIT_L(0); PG8_BAR; PG8_MMA(1, 0, At, B0); PG8_MMA(1, 1, At, B1); PG8_BAR; PG8_SCHED;
;             PG8_LDB(B0, 1, 0); PG8_LDB(B1, 1, 1); PG8_SCHED; PG8_LDA(At, 1, 0); PG8_STAGE(PG8_SA(0, 1), a2 + hstepA, voffA);
;             PG8_WAIT_V(8); PG8_WAIT_L(0); PG8_BAR; PG8_MMA(0, 0, At, B0); PG8_MMA(0, 1, At, B1); PG8_BAR; PG8_SCHED;
	s_add_i32 s48, s51, s17
	v_lshl_add_u64 v[160:161], s[76:77], 0, v[0:1]
	s_mov_b32 m0, s48
	ds_read_b128 v[200:203], v147 offset:16384
	ds_read_b128 v[204:207], v147 offset:17408
	ds_read_b128 v[208:211], v147 offset:18432
	ds_read_b128 v[212:215], v147 offset:19456
	ds_read_b128 v[216:219], v147 offset:20480
	ds_read_b128 v[220:223], v147 offset:21504
	ds_read_b128 v[224:227], v147 offset:22528
	ds_read_b128 v[228:231], v147 offset:23552
	global_load_lds_dwordx4 v[160:161], off
	s_add_i32 m0, s48, 0x2000
	s_add_u32 s48, s76, 0x40000
	v_lshl_add_u64 v[178:179], s[76:77], 0, v[134:135]
	s_addc_u32 s49, s77, 0
	s_add_i32 s51, s52, s17
	global_load_lds_dwordx4 v[178:179], off
	v_lshl_add_u64 v[188:189], s[48:49], 0, v[0:1]
	s_mov_b32 m0, s51
	v_lshl_add_u64 v[190:191], s[78:79], 0, v[132:133]
	global_load_lds_dwordx4 v[188:189], off
	v_lshl_add_u64 v[188:189], s[48:49], 0, v[134:135]
	s_add_i32 m0, s51, 0x2000
	s_nop 0
	global_load_lds_dwordx4 v[188:189], off
	v_lshl_add_u64 v[188:189], s[78:79], 0, v[130:131]
	s_mov_b32 m0, s22
	s_nop 0
	global_load_lds_dwordx4 v[188:189], off
	s_mov_b32 m0, s26
	s_nop 0
	global_load_lds_dwordx4 v[190:191], off
	s_waitcnt vmcnt(8)
	s_waitcnt lgkmcnt(0)
	s_barrier
	s_waitcnt lgkmcnt(0)
	v_mfma_f32_16x16x32_bf16 v[62:65], v[140:143], v[200:203], v[62:65]
	v_mfma_f32_16x16x32_bf16 v[58:61], v[152:155], v[200:203], v[58:61]
	v_mfma_f32_16x16x32_bf16 v[46:49], v[140:143], v[208:211], v[46:49]
	v_mfma_f32_16x16x32_bf16 v[42:45], v[152:155], v[208:211], v[42:45]
	v_mfma_f32_16x16x32_bf16 v[30:33], v[140:143], v[216:219], v[30:33]
	v_mfma_f32_16x16x32_bf16 v[26:29], v[152:155], v[216:219], v[26:29]
	v_mfma_f32_16x16x32_bf16 v[14:17], v[140:143], v[224:227], v[14:17]
	v_mfma_f32_16x16x32_bf16 v[10:13], v[152:155], v[224:227], v[10:13]
	v_mfma_f32_16x16x32_bf16 v[62:65], v[148:151], v[204:207], v[62:65]
	v_mfma_f32_16x16x32_bf16 v[58:61], v[156:159], v[204:207], v[58:61]
	v_mfma_f32_16x16x32_bf16 v[46:49], v[148:151], v[212:215], v[46:49]
	v_mfma_f32_16x16x32_bf16 v[42:45], v[156:159], v[212:215], v[42:45]
	v_mfma_f32_16x16x32_bf16 v[30:33], v[148:151], v[220:223], v[30:33]
	v_mfma_f32_16x16x32_bf16 v[26:29], v[156:159], v[220:223], v[26:29]
	v_mfma_f32_16x16x32_bf16 v[14:17], v[148:151], v[228:231], v[14:17]
	v_mfma_f32_16x16x32_bf16 v[10:13], v[156:159], v[228:231], v[10:13]
	v_mfma_f32_16x16x32_bf16 v[54:57], v[164:167], v[200:203], v[54:57]
	v_mfma_f32_16x16x32_bf16 v[50:53], v[174:177], v[200:203], v[50:53]
	v_mfma_f32_16x16x32_bf16 v[38:41], v[164:167], v[208:211], v[38:41]
	v_mfma_f32_16x16x32_bf16 v[34:37], v[174:177], v[208:211], v[34:37]
	v_mfma_f32_16x16x32_bf16 v[22:25], v[164:167], v[216:219], v[22:25]
	v_mfma_f32_16x16x32_bf16 v[18:21], v[174:177], v[216:219], v[18:21]
	v_mfma_f32_16x16x32_bf16 v[6:9], v[164:167], v[224:227], v[6:9]
	v_mfma_f32_16x16x32_bf16 v[2:5], v[174:177], v[224:227], v[2:5]
	v_mfma_f32_16x16x32_bf16 v[54:57], v[170:173], v[204:207], v[54:57]
	v_mfma_f32_16x16x32_bf16 v[50:53], v[196:199], v[204:207], v[50:53]
	v_mfma_f32_16x16x32_bf16 v[38:41], v[170:173], v[212:215], v[38:41]
	v_mfma_f32_16x16x32_bf16 v[34:37], v[196:199], v[212:215], v[34:37]
	v_mfma_f32_16x16x32_bf16 v[22:25], v[170:173], v[220:223], v[22:25]
	v_mfma_f32_16x16x32_bf16 v[18:21], v[196:199], v[220:223], v[18:21]
	v_mfma_f32_16x16x32_bf16 v[6:9], v[170:173], v[228:231], v[6:9]
	v_mfma_f32_16x16x32_bf16 v[2:5], v[196:199], v[228:231], v[2:5]
	s_barrier
	s_add_i32 s51, 0, 0x18000
	s_add_i32 s52, 0, 0x1c000
	v_add_u32_e32 v156, s51, v145
	v_add_u32_e32 v168, s52, v145
	ds_read_b128 v[140:143], v156
	ds_read_b128 v[148:151], v156 offset:1024
	ds_read_b128 v[152:155], v156 offset:2048
	ds_read_b128 v[156:159], v156 offset:3072
	ds_read_b128 v[164:167], v168
	ds_read_b128 v[170:173], v168 offset:1024
	ds_read_b128 v[174:177], v168 offset:2048
	ds_read_b128 v[196:199], v168 offset:3072
	s_add_u32 s48, s78, 0x40000
	s_addc_u32 s49, s79, 0
	s_mov_b32 m0, s28
	v_lshl_add_u64 v[232:233], s[48:49], 0, v[130:131]
	ds_read_b128 v[200:203], v147 offset:32768
	ds_read_b128 v[204:207], v147 offset:33792
	ds_read_b128 v[208:211], v147 offset:34816
	ds_read_b128 v[212:215], v147 offset:35840
	ds_read_b128 v[216:219], v147 offset:36864
	ds_read_b128 v[220:223], v147 offset:37888
	ds_read_b128 v[224:227], v147 offset:38912
	ds_read_b128 v[228:231], v147 offset:39936
	global_load_lds_dwordx4 v[232:233], off
	v_lshl_add_u64 v[232:233], s[48:49], 0, v[132:133]
	s_mov_b32 m0, s30
	s_nop 0
	global_load_lds_dwordx4 v[232:233], off
	s_waitcnt vmcnt(8)
	s_waitcnt lgkmcnt(0)
	s_barrier
; #define PG8_STAGE(bufoff, gbase, voff) do { _Pragma("unroll") for (int _i = 0; _i < 2; ++_i) \
;         __builtin_amdgcn_global_load_lds((const unsigned*)((const char*)(gbase) + (voff)[_i]), (LAS unsigned*)(lds + (bufoff) + ldsw + _i * 8192), 16, 0, 0); } while (0)
; #define PG8_LDA(dst, b, h) do { _Pragma("unroll") for (int m = 0; m < 4; ++m) _Pragma("unroll") for (int k = 0; k < 2; ++k) dst[m][k] = *(const LAS bf16x8*)(lds + PG8_SA(b, h) + aoff + m * 2048 + k * 1024); } while (0)
; #define PG8_MMA(ai, bj, At, Bt) do { __builtin_amdgcn_s_setprio(1); _Pragma("unroll") for (int m = 0; m < 4; ++m) _Pragma("unroll") for (int n = 0; n < 2; ++n) _Pragma("unroll") for (int k = 0; k < 2; ++k) \
;         acc[ai][bj][m][n] = __builtin_amdgcn_mfma_f32_16x16x32_bf16(Bt[n][k], At[m][k], acc[ai][bj][m][n], 0, 0, 0); __builtin_amdgcn_s_setprio(0); } while (0)
; #define PG8_WAIT_V(n) asm volatile("s_waitcnt vmcnt(" #n ")" ::: "memory")
; #define PG8_WAIT_L(n) asm volatile("s_waitcnt lgkmcnt(" #n ")" ::: "memory")
; #define PG8_BAR __builtin_amdgcn_s_barrier()
; #define PG8_SCHED __builtin_amdgcn_sched_barrier(0)
; template <class Epi>
; DI void gemm_phase(LAS unsigned char* lds, int tid, const Gemm g, const Order& S, const Epi& E) {
;     ...
;             PG8_WAIT_V(8); PG8_WAIT_L(0); PG8_BAR; PG8_MMA(0, 0, At, B0); PG8_MMA(0, 1, At, B1); PG8_BAR; PG8_SCHED;
;             PG8_LDA(At, 1, 1); PG8_STAGE(PG8_SB(1, 0), b3, voffB); PG8_STAGE(PG8_SB(1, 1), b3 + hstepB, voffB); PG8_STAGE(PG8_SA(1, 0), a3, voffA);
;             PG8_WAIT_V(8); PG8_WAIT_L(0); PG8_BAR; PG8_MMA(1, 0, At, B0); PG8_MMA(1, 1, At, B1); PG8_BAR; PG8_SCHED;
;         }
;         if (wr == 0) PG8_BAR;
	s_waitcnt lgkmcnt(0)
	v_mfma_f32_16x16x32_bf16 v[126:129], v[140:143], v[200:203], v[126:129]
	v_mfma_f32_16x16x32_bf16 v[122:125], v[152:155], v[200:203], v[122:125]
	v_mfma_f32_16x16x32_bf16 v[110:113], v[140:143], v[208:211], v[110:113]
	v_mfma_f32_16x16x32_bf16 v[106:109], v[152:155], v[208:211], v[106:109]
	v_mfma_f32_16x16x32_bf16 v[94:97], v[140:143], v[216:219], v[94:97]
	v_mfma_f32_16x16x32_bf16 v[90:93], v[152:155], v[216:219], v[90:93]
	v_mfma_f32_16x16x32_bf16 v[78:81], v[140:143], v[224:227], v[78:81]
	v_mfma_f32_16x16x32_bf16 v[74:77], v[152:155], v[224:227], v[74:77]
	v_mfma_f32_16x16x32_bf16 v[126:129], v[148:151], v[204:207], v[126:129]
	v_mfma_f32_16x16x32_bf16 v[122:125], v[156:159], v[204:207], v[122:125]
	v_mfma_f32_16x16x32_bf16 v[110:113], v[148:151], v[212:215], v[110:113]
	v_mfma_f32_16x16x32_bf16 v[106:109], v[156:159], v[212:215], v[106:109]
	v_mfma_f32_16x16x32_bf16 v[94:97], v[148:151], v[220:223], v[94:97]
	v_mfma_f32_16x16x32_bf16 v[90:93], v[156:159], v[220:223], v[90:93]
	v_mfma_f32_16x16x32_bf16 v[78:81], v[148:151], v[228:231], v[78:81]
	v_mfma_f32_16x16x32_bf16 v[74:77], v[156:159], v[228:231], v[74:77]
	v_mfma_f32_16x16x32_bf16 v[118:121], v[164:167], v[200:203], v[118:121]
	v_mfma_f32_16x16x32_bf16 v[114:117], v[174:177], v[200:203], v[114:117]
	v_mfma_f32_16x16x32_bf16 v[102:105], v[164:167], v[208:211], v[102:105]
	v_mfma_f32_16x16x32_bf16 v[98:101], v[174:177], v[208:211], v[98:101]
	v_mfma_f32_16x16x32_bf16 v[86:89], v[164:167], v[216:219], v[86:89]
	v_mfma_f32_16x16x32_bf16 v[82:85], v[174:177], v[216:219], v[82:85]
	v_mfma_f32_16x16x32_bf16 v[70:73], v[164:167], v[224:227], v[70:73]
	v_mfma_f32_16x16x32_bf16 v[66:69], v[174:177], v[224:227], v[66:69]
	v_mfma_f32_16x16x32_bf16 v[118:121], v[170:173], v[204:207], v[118:121]
	v_mfma_f32_16x16x32_bf16 v[114:117], v[196:199], v[204:207], v[114:117]
	v_mfma_f32_16x16x32_bf16 v[102:105], v[170:173], v[212:215], v[102:105]
	v_mfma_f32_16x16x32_bf16 v[98:101], v[196:199], v[212:215], v[98:101]
	v_mfma_f32_16x16x32_bf16 v[86:89], v[170:173], v[220:223], v[86:89]
	v_mfma_f32_16x16x32_bf16 v[82:85], v[196:199], v[220:223], v[82:85]
	v_mfma_f32_16x16x32_bf16 v[70:73], v[170:173], v[228:231], v[70:73]
	v_mfma_f32_16x16x32_bf16 v[66:69], v[196:199], v[228:231], v[66:69]
	s_barrier
	s_add_i32 s48, s51, s17
	v_lshl_add_u64 v[160:161], v[160:161], 0, s[24:25]
	s_mov_b32 m0, s48
	ds_read_b128 v[200:203], v147 offset:49152
	ds_read_b128 v[204:207], v147 offset:50176
	ds_read_b128 v[208:211], v147 offset:51200
	ds_read_b128 v[212:215], v147 offset:52224
	ds_read_b128 v[216:219], v147 offset:53248
	ds_read_b128 v[220:223], v147 offset:54272
	ds_read_b128 v[224:227], v147 offset:55296
	ds_read_b128 v[228:231], v147 offset:56320
	global_load_lds_dwordx4 v[160:161], off
	s_add_i32 m0, s48, 0x2000
	s_add_u32 s48, s76, 0x40080
	v_lshl_add_u64 v[160:161], v[178:179], 0, s[24:25]
	s_addc_u32 s49, s77, 0
	s_add_i32 s51, s52, s17
	global_load_lds_dwordx4 v[160:161], off
	v_lshl_add_u64 v[160:161], s[48:49], 0, v[0:1]
	s_mov_b32 m0, s51
	s_nop 0
	global_load_lds_dwordx4 v[160:161], off
	v_lshl_add_u64 v[160:161], s[48:49], 0, v[134:135]
	s_add_i32 m0, s51, 0x2000
	s_nop 0
	global_load_lds_dwordx4 v[160:161], off
	v_lshl_add_u64 v[160:161], v[188:189], 0, s[24:25]
	s_mov_b32 m0, s34
	s_nop 0
	global_load_lds_dwordx4 v[160:161], off
	v_lshl_add_u64 v[160:161], v[190:191], 0, s[24:25]
	s_mov_b32 m0, s36
	s_nop 0
	global_load_lds_dwordx4 v[160:161], off
	s_waitcnt vmcnt(8)
	s_waitcnt lgkmcnt(0)
	s_barrier
	s_waitcnt lgkmcnt(0)
	v_mfma_f32_16x16x32_bf16 v[62:65], v[140:143], v[200:203], v[62:65]
	v_mfma_f32_16x16x32_bf16 v[58:61], v[152:155], v[200:203], v[58:61]
	v_mfma_f32_16x16x32_bf16 v[46:49], v[140:143], v[208:211], v[46:49]
	v_mfma_f32_16x16x32_bf16 v[42:45], v[152:155], v[208:211], v[42:45]
	v_mfma_f32_16x16x32_bf16 v[30:33], v[140:143], v[216:219], v[30:33]
	v_mfma_f32_16x16x32_bf16 v[26:29], v[152:155], v[216:219], v[26:29]
	v_mfma_f32_16x16x32_bf16 v[14:17], v[140:143], v[224:227], v[14:17]
	v_mfma_f32_16x16x32_bf16 v[10:13], v[152:155], v[224:227], v[10:13]
	v_mfma_f32_16x16x32_bf16 v[62:65], v[148:151], v[204:207], v[62:65]
	v_mfma_f32_16x16x32_bf16 v[58:61], v[156:159], v[204:207], v[58:61]
	v_mfma_f32_16x16x32_bf16 v[46:49], v[148:151], v[212:215], v[46:49]
	v_mfma_f32_16x16x32_bf16 v[42:45], v[156:159], v[212:215], v[42:45]
	v_mfma_f32_16x16x32_bf16 v[30:33], v[148:151], v[220:223], v[30:33]
	v_mfma_f32_16x16x32_bf16 v[26:29], v[156:159], v[220:223], v[26:29]
	v_mfma_f32_16x16x32_bf16 v[14:17], v[148:151], v[228:231], v[14:17]
	v_mfma_f32_16x16x32_bf16 v[10:13], v[156:159], v[228:231], v[10:13]
	v_mfma_f32_16x16x32_bf16 v[54:57], v[164:167], v[200:203], v[54:57]
	v_mfma_f32_16x16x32_bf16 v[50:53], v[174:177], v[200:203], v[50:53]
	v_mfma_f32_16x16x32_bf16 v[38:41], v[164:167], v[208:211], v[38:41]
	v_mfma_f32_16x16x32_bf16 v[34:37], v[174:177], v[208:211], v[34:37]
	v_mfma_f32_16x16x32_bf16 v[22:25], v[164:167], v[216:219], v[22:25]
	v_mfma_f32_16x16x32_bf16 v[18:21], v[174:177], v[216:219], v[18:21]
	v_mfma_f32_16x16x32_bf16 v[6:9], v[164:167], v[224:227], v[6:9]
	v_mfma_f32_16x16x32_bf16 v[2:5], v[174:177], v[224:227], v[2:5]
	v_mfma_f32_16x16x32_bf16 v[54:57], v[170:173], v[204:207], v[54:57]
	v_mfma_f32_16x16x32_bf16 v[50:53], v[196:199], v[204:207], v[50:53]
	v_mfma_f32_16x16x32_bf16 v[38:41], v[170:173], v[212:215], v[38:41]
	v_mfma_f32_16x16x32_bf16 v[34:37], v[196:199], v[212:215], v[34:37]
	v_mfma_f32_16x16x32_bf16 v[22:25], v[170:173], v[220:223], v[22:25]
	v_mfma_f32_16x16x32_bf16 v[18:21], v[196:199], v[220:223], v[18:21]
	v_mfma_f32_16x16x32_bf16 v[6:9], v[170:173], v[228:231], v[6:9]
	v_mfma_f32_16x16x32_bf16 v[2:5], v[196:199], v[228:231], v[2:5]
	s_barrier
	s_add_i32 s47, s47, 2
	s_add_u32 s74, s74, 0x100
	s_addc_u32 s75, s75, 0
	s_add_u32 s45, s45, 0x100
	s_addc_u32 s46, s46, 0
	s_cmp_gt_u32 s47, 13
	s_cbranch_scc0 .LBB0_513
	s_and_b64 vcc, exec, s[8:9]
	s_cbranch_vccz .LBB0_516
	s_barrier

; #define GRID_SYNC() do { nbar += (unsigned)gridDim.x; grid_barrier(barw, nbar); } while (0)
; __global__ void __launch_bounds__(512, 2) fwd_megakernel(Args args) {
;     ...
;             if (!(op == 4 || op == 6 || op == 7 || skip0)) GRID_SYNC();
.LBB0_578:
	s_setprio 0
	s_waitcnt lgkmcnt(0)
	s_load_dword s13, s[0:1], 0xa8
	v_readlane_b32 s22, v255, 25
